# split barrier (ret_scan arrive / ret_output wait) plus ret_output gate loads issued four at a time per query tile
# baseline (speedup 1.0000x reference)
; #define LAS __attribute__((address_space(3)))
; __device__ __forceinline__ unsigned pk2(float lo, float hi) { return pg8::cvt_pk_bf16(lo, hi); }
; __device__ __forceinline__ float ex2(float x) { return __builtin_amdgcn_exp2f(x); }
; __device__ __forceinline__ s16x4 tr16(const LAS unsigned char* p) { return __builtin_bit_cast(s16x4, __builtin_amdgcn_ds_read_tr16_b64_v4i16((LAS s16x4*)p)); }
; #define MFMA16(a, b, c) __builtin_amdgcn_mfma_f32_16x16x32_bf16(a, b, c, 0, 0, 0)
; __device__ __forceinline__ void stage_v_regs(const u32x4 (&v)[4], LAS unsigned char* vimg, int lane, bf16x8 (&vf)[4]) {
;     LAS unsigned char* d = vimg + (lane >> 3) * VPITCH + (lane & 7) * 16;
; #pragma unroll
;     for (int i = 0; i < 4; ++i) *(LAS u32x4*)(d + 8 * i * VPITCH) = v[i];
;     asm volatile("" ::: "memory");
;     const int i16 = lane & 15, quad = lane >> 4;
;     const LAS unsigned char* b = vimg + (4 * quad + (i16 >> 2)) * VPITCH + (i16 & 3) * 8;
; #pragma unroll
;     for (int nn = 0; nn < 4; ++nn) { const s16x4 lo = tr16(b + nn * 32), hi = tr16(b + 16 * VPITCH + nn * 32); vf[nn] = (bf16x8){lo[0], lo[1], lo[2], lo[3], hi[0], hi[1], hi[2], hi[3]}; }
;     asm volatile("" ::: "memory");
; __device__ __forceinline__ void ret_output(Frame& F, const Trunk& T, int layer) {
;     ...
;         for (int t = 0; t < 4; ++t) {
;             if (t + 1 < 4) tile_load_r(nxt, kp, vp, t + 1, lane);
;             bf16x8 vf[4]; stage_v_regs(cur.v, vimg, lane, vf);
;             const int sg0 = 32 * t + 4 * quad - i16 - 64 * half;
; #pragma unroll
;             for (int qt = 0; qt < 4; ++qt) { float p[8];
; #pragma unroll
;                 for (int st = 0; st < 2; ++st) { const f32x4 s = MFMA16(cur.k[st], qf[qt], z4);
; #pragma unroll
;                     for (int jj = 0; jj < 4; ++jj) { const int nd = sg0 + 16 * st + jj - 16 * qt;
;                         const float w = nd <= 0 ? ex2(lgf * (float)(-nd)) : ex2(lgb * (float)nd); p[4 * st + jj] = s[jj] * w; } }
;                 const u32x4 pw = {pk2(p[0], p[1]), pk2(p[2], p[3]), pk2(p[4], p[5]), pk2(p[6], p[7])}; const bf16x8 pf = __builtin_bit_cast(bf16x8, pw);
; #pragma unroll
;                 for (int nn = 0; nn < 4; ++nn) o[qt][nn] = MFMA16(vf[nn], pf, o[qt][nn]); }
.LBB0_728:
	v_add_u32_e32 v74, s0, v72
	v_sub_u32_e32 v75, 0, v74
	v_cmp_gt_i32_e32 vcc, 1, v74
	v_max_i32_e32 v75, v74, v75
	v_add_u32_e32 v151, 18, v73
	s_waitcnt vmcnt(10)
	v_cndmask_b32_e32 v149, v208, v207, vcc
	v_add_u32_e32 v153, 1, v74
	v_cmp_gt_i32_e32 vcc, 0, v74
	v_cvt_f32_u32_e32 v75, v75
	v_add_u32_e32 v162, 2, v74
	v_cndmask_b32_e32 v155, v153, v151, vcc
	v_cvt_f32_u32_e32 v155, v155
	v_mul_f32_e32 v75, v149, v75
	v_cndmask_b32_e32 v149, v208, v207, vcc
	v_cmp_gt_i32_e32 vcc, -1, v74
	v_mul_f32_e32 v149, v149, v155
	v_add_u32_e32 v155, 17, v73
	v_cndmask_b32_e32 v163, v162, v155, vcc
	v_cndmask_b32_e32 v167, v208, v207, vcc
	v_add_u32_e32 v200, 16, v73
	v_add_u32_e32 v201, 3, v74
	v_cmp_gt_i32_e32 vcc, -2, v74
	v_cvt_f32_u32_e32 v163, v163
	v_add_u32_e32 v214, 16, v74
	v_cndmask_b32_e32 v209, v201, v200, vcc
	v_cvt_f32_u32_e32 v209, v209
	v_mul_f32_e32 v163, v167, v163
	v_cndmask_b32_e32 v167, v208, v207, vcc
	v_cmp_gt_i32_e32 vcc, -15, v74
	v_mul_f32_e32 v167, v167, v209
	v_add_u32_e32 v209, 3, v73
	v_cndmask_b32_e32 v209, v214, v209, vcc
	v_cndmask_b32_e32 v214, v208, v207, vcc
	v_add_u32_e32 v215, 2, v73
	v_add_u32_e32 v216, 17, v74
	v_cmp_gt_i32_e32 vcc, -16, v74
	v_cvt_f32_u32_e32 v209, v209
	s_waitcnt vmcnt(3)
	v_mfma_f32_16x16x32_bf16 v[210:213], v[48:51], v[116:119], 0
	v_cndmask_b32_e32 v215, v216, v215, vcc
	v_cvt_f32_u32_e32 v215, v215
	v_mul_f32_e32 v209, v214, v209
	v_cndmask_b32_e32 v214, v208, v207, vcc
	v_add_u32_e32 v216, 18, v74
	v_mul_f32_e32 v214, v214, v215
	v_add_u32_e32 v215, 1, v73
	v_cmp_gt_i32_e32 vcc, s80, v74
	v_exp_f32_e32 v75, v75
	v_exp_f32_e32 v149, v149
	v_exp_f32_e32 v163, v163
	v_exp_f32_e32 v167, v167
	v_cndmask_b32_e32 v215, v216, v215, vcc
	v_cvt_f32_u32_e32 v215, v215
	v_mul_f32_e32 v75, v75, v210
	v_mul_f32_e32 v149, v149, v211
	v_mul_f32_e32 v163, v163, v212
	v_mul_f32_e32 v167, v167, v213
	v_mfma_f32_16x16x32_bf16 v[210:213], v[44:47], v[116:119], 0
	v_exp_f32_e32 v209, v209
	v_cndmask_b32_e32 v216, v208, v207, vcc
	v_add_u32_e32 v217, 19, v74
	v_cmp_gt_i32_e32 vcc, s81, v74
	v_mul_f32_e32 v215, v216, v215
	ds_write_b128 v205, v[52:55]
	ds_write_b128 v205, v[56:59] offset:1152
	ds_write_b128 v205, v[60:63] offset:2304
	ds_write_b128 v205, v[64:67] offset:3456
	v_cndmask_b32_e32 v217, v217, v73, vcc
	v_exp_f32_e32 v214, v214
	v_cvt_f32_u32_e32 v217, v217
	v_exp_f32_e32 v215, v215
	ds_read_b64_tr_b16 v[56:57], v206
	ds_read_b64_tr_b16 v[52:53], v206 offset:32
	ds_read_b64_tr_b16 v[60:61], v206 offset:64
	ds_read_b64_tr_b16 v[64:65], v206 offset:96
	ds_read_b64_tr_b16 v[58:59], v206 offset:2304
	ds_read_b64_tr_b16 v[54:55], v206 offset:2336
	ds_read_b64_tr_b16 v[62:63], v206 offset:2368
	ds_read_b64_tr_b16 v[66:67], v206 offset:2400
	v_mul_f32_e32 v209, v209, v210
	s_nop 0
	v_cvt_pk_bf16_f32 v210, v75, v149
	v_add_u32_e32 v75, -16, v74
	v_cndmask_b32_e32 v216, v208, v207, vcc
	v_sub_u32_e32 v149, 16, v74
	v_cmp_gt_i32_e32 vcc, 1, v75
	v_mul_f32_e32 v216, v216, v217
	v_mul_f32_e32 v214, v214, v211
	v_mul_f32_e32 v215, v215, v212
	s_nop 0
	v_cvt_pk_bf16_f32 v211, v163, v167
	s_nop 0
	v_cvt_pk_bf16_f32 v212, v209, v214
	v_max_i32_e32 v149, v75, v149
	v_cndmask_b32_e32 v163, v208, v207, vcc
	v_add_u32_e32 v167, 34, v73
	v_add_u32_e32 v209, -15, v74
	v_cmp_gt_i32_e32 vcc, 0, v75
	v_exp_f32_e32 v216, v216
	v_cvt_f32_u32_e32 v149, v149
	v_cndmask_b32_e32 v214, v209, v167, vcc
	v_cvt_f32_u32_e32 v214, v214
	v_mul_f32_e32 v213, v216, v213
	v_mul_f32_e32 v149, v163, v149
	v_cndmask_b32_e32 v163, v208, v207, vcc
	s_nop 0
	v_cvt_pk_bf16_f32 v213, v215, v213
	v_mul_f32_e32 v163, v163, v214
	v_add_u32_e32 v214, 33, v73
	v_add_u32_e32 v215, -14, v74
	v_cmp_gt_i32_e32 vcc, -1, v75
	v_add_u32_e32 v218, 32, v73
	v_add_u32_e32 v219, -13, v74
	v_cndmask_b32_e32 v216, v215, v214, vcc
	v_cndmask_b32_e32 v217, v208, v207, vcc
	v_cmp_gt_i32_e32 vcc, -2, v75
	v_cvt_f32_u32_e32 v216, v216
	s_waitcnt lgkmcnt(3)
	v_mfma_f32_16x16x32_bf16 v[132:135], v[56:59], v[210:213], v[132:135]
	v_cndmask_b32_e32 v220, v219, v218, vcc
	v_cvt_f32_u32_e32 v220, v220
	v_mul_f32_e32 v216, v217, v216
	v_cndmask_b32_e32 v217, v208, v207, vcc
	v_cmp_gt_i32_e32 vcc, -15, v75
	v_mul_f32_e32 v217, v217, v220
	v_add_u32_e32 v220, 19, v73
	v_cndmask_b32_e32 v220, v74, v220, vcc
	v_cvt_f32_u32_e32 v220, v220
	v_cndmask_b32_e32 v221, v208, v207, vcc
	v_cmp_gt_i32_e32 vcc, -16, v75
	s_waitcnt lgkmcnt(2)
	v_mfma_f32_16x16x32_bf16 v[128:131], v[52:55], v[210:213], v[128:131]
	v_exp_f32_e32 v149, v149
	v_cndmask_b32_e32 v151, v153, v151, vcc
	v_mul_f32_e32 v153, v221, v220
	v_cndmask_b32_e32 v220, v208, v207, vcc
	v_cmp_gt_i32_e32 vcc, s80, v75
	v_cvt_f32_u32_e32 v151, v151
	s_waitcnt lgkmcnt(1)
	v_mfma_f32_16x16x32_bf16 v[124:127], v[60:63], v[210:213], v[124:127]
	v_cndmask_b32_e32 v155, v162, v155, vcc
	v_cndmask_b32_e32 v162, v208, v207, vcc
	v_cmp_gt_i32_e32 vcc, s81, v75
	v_cvt_f32_u32_e32 v155, v155
	s_waitcnt lgkmcnt(0)
	v_mfma_f32_16x16x32_bf16 v[120:123], v[64:67], v[210:213], v[120:123]
	v_cndmask_b32_e32 v200, v201, v200, vcc
	v_exp_f32_e32 v163, v163
	v_exp_f32_e32 v216, v216
	s_waitcnt vmcnt(2)
; __device__ __forceinline__ unsigned pk2(float lo, float hi) { return pg8::cvt_pk_bf16(lo, hi); }
; __device__ __forceinline__ float ex2(float x) { return __builtin_amdgcn_exp2f(x); }
; #define MFMA16(a, b, c) __builtin_amdgcn_mfma_f32_16x16x32_bf16(a, b, c, 0, 0, 0)
; __device__ __forceinline__ void ret_output(Frame& F, const Trunk& T, int layer) {
;     ...
;             const int sg0 = 32 * t + 4 * quad - i16 - 64 * half;
; #pragma unroll
;             for (int qt = 0; qt < 4; ++qt) { float p[8];
; #pragma unroll
;                 for (int st = 0; st < 2; ++st) { const f32x4 s = MFMA16(cur.k[st], qf[qt], z4);
; #pragma unroll
;                     for (int jj = 0; jj < 4; ++jj) { const int nd = sg0 + 16 * st + jj - 16 * qt;
;                         const float w = nd <= 0 ? ex2(lgf * (float)(-nd)) : ex2(lgb * (float)nd); p[4 * st + jj] = s[jj] * w; } }
;                 const u32x4 pw = {pk2(p[0], p[1]), pk2(p[2], p[3]), pk2(p[4], p[5]), pk2(p[6], p[7])}; const bf16x8 pf = __builtin_bit_cast(bf16x8, pw);
; #pragma unroll
;                 for (int nn = 0; nn < 4; ++nn) o[qt][nn] = MFMA16(vf[nn], pf, o[qt][nn]); }
;             cur = nxt;
	v_mfma_f32_16x16x32_bf16 v[210:213], v[48:51], v[96:99], 0
	v_exp_f32_e32 v217, v217
	v_cvt_f32_u32_e32 v200, v200
	v_mul_f32_e32 v151, v220, v151
	v_mul_f32_e32 v155, v162, v155
	v_cndmask_b32_e32 v162, v208, v207, vcc
	s_nop 2
	v_mul_f32_e32 v149, v149, v210
	v_mul_f32_e32 v163, v163, v211
	v_mul_f32_e32 v216, v216, v212
	v_mul_f32_e32 v217, v217, v213
	v_mfma_f32_16x16x32_bf16 v[210:213], v[44:47], v[96:99], 0
	v_exp_f32_e32 v153, v153
	v_exp_f32_e32 v151, v151
	v_mul_f32_e32 v162, v162, v200
	v_exp_f32_e32 v155, v155
	v_exp_f32_e32 v162, v162
	s_nop 2
	v_mul_f32_e32 v153, v153, v210
	v_mul_f32_e32 v151, v151, v211
	s_nop 0
	v_cvt_pk_bf16_f32 v210, v149, v163
	v_subrev_u32_e32 v149, 32, v74
	v_mul_f32_e32 v155, v155, v212
	v_mul_f32_e32 v162, v162, v213
	s_nop 0
	v_cvt_pk_bf16_f32 v211, v216, v217
	s_nop 0
	v_cvt_pk_bf16_f32 v212, v153, v151
	v_sub_u32_e32 v151, 32, v74
	v_cmp_gt_i32_e32 vcc, 1, v149
	s_nop 0
	v_cvt_pk_bf16_f32 v213, v155, v162
	v_max_i32_e32 v151, v149, v151
	v_add_u32_e32 v155, 50, v73
	v_cndmask_b32_e32 v153, v208, v207, vcc
	v_subrev_u32_e32 v162, 31, v74
	v_cmp_gt_i32_e32 vcc, 0, v149
	v_cvt_f32_u32_e32 v151, v151
	v_subrev_u32_e32 v200, 30, v74
	v_cndmask_b32_e32 v163, v162, v155, vcc
	v_cvt_f32_u32_e32 v163, v163
	v_mul_f32_e32 v151, v153, v151
	v_cndmask_b32_e32 v153, v208, v207, vcc
	v_cmp_gt_i32_e32 vcc, -1, v149
	v_mul_f32_e32 v153, v153, v163
	v_add_u32_e32 v163, 49, v73
	v_cndmask_b32_e32 v201, v200, v163, vcc
	v_cndmask_b32_e32 v216, v208, v207, vcc
	v_add_u32_e32 v217, 48, v73
	v_subrev_u32_e32 v220, 29, v74
	v_cmp_gt_i32_e32 vcc, -2, v149
	v_cvt_f32_u32_e32 v201, v201
	v_mfma_f32_16x16x32_bf16 v[112:115], v[56:59], v[210:213], v[112:115]
	v_cndmask_b32_e32 v221, v220, v217, vcc
	v_cvt_f32_u32_e32 v221, v221
	v_mul_f32_e32 v201, v216, v201
	v_cndmask_b32_e32 v216, v208, v207, vcc
	v_cmp_gt_i32_e32 vcc, -15, v149
	v_mul_f32_e32 v216, v216, v221
	v_add_u32_e32 v221, 35, v73
	v_cndmask_b32_e32 v75, v75, v221, vcc
	v_cndmask_b32_e32 v221, v208, v207, vcc
	v_cmp_gt_i32_e32 vcc, -16, v149
	v_cvt_f32_u32_e32 v75, v75
	v_mfma_f32_16x16x32_bf16 v[108:111], v[52:55], v[210:213], v[108:111]
	v_cndmask_b32_e32 v167, v209, v167, vcc
	v_cvt_f32_u32_e32 v167, v167
	v_cndmask_b32_e32 v209, v208, v207, vcc
	v_cmp_gt_i32_e32 vcc, s80, v149
	v_mfma_f32_16x16x32_bf16 v[104:107], v[60:63], v[210:213], v[104:107]
	v_mul_f32_e32 v167, v209, v167
	v_cndmask_b32_e32 v209, v215, v214, vcc
	v_exp_f32_e32 v151, v151
	v_mfma_f32_16x16x32_bf16 v[100:103], v[64:67], v[210:213], v[100:103]
	v_exp_f32_e32 v153, v153
	v_exp_f32_e32 v201, v201
	v_exp_f32_e32 v216, v216
	s_waitcnt vmcnt(1)
	v_mfma_f32_16x16x32_bf16 v[210:213], v[48:51], v[76:79], 0
	v_cvt_f32_u32_e32 v209, v209
	v_mul_f32_e32 v75, v221, v75
	v_cndmask_b32_e32 v214, v208, v207, vcc
	v_exp_f32_e32 v75, v75
	v_mul_f32_e32 v209, v214, v209
	s_nop 2
	v_mul_f32_e32 v151, v151, v210
	v_mul_f32_e32 v153, v153, v211
	v_mul_f32_e32 v201, v201, v212
	v_mul_f32_e32 v216, v216, v213
	v_mfma_f32_16x16x32_bf16 v[210:213], v[44:47], v[76:79], 0
	v_exp_f32_e32 v167, v167
	v_exp_f32_e32 v209, v209
	v_cmp_gt_i32_e32 vcc, s81, v149
	s_waitcnt vmcnt(0)
	v_mfma_f32_16x16x32_bf16 v[48:51], v[48:51], v[24:27], 0
	s_add_i32 s0, s0, 32
	v_cndmask_b32_e32 v215, v219, v218, vcc
	v_cvt_f32_u32_e32 v215, v215
	v_mul_f32_e32 v75, v75, v210
	v_mul_f32_e32 v167, v167, v211
	v_mul_f32_e32 v209, v209, v212
	s_nop 0
	v_cvt_pk_bf16_f32 v210, v151, v153
	s_nop 0
	v_cvt_pk_bf16_f32 v211, v201, v216
	s_nop 0
	v_cvt_pk_bf16_f32 v212, v75, v167
	v_subrev_u32_e32 v75, 48, v74
	v_cndmask_b32_e32 v214, v208, v207, vcc
	v_sub_u32_e32 v151, 48, v74
	v_cmp_gt_i32_e32 vcc, 1, v75
	v_max_i32_e32 v151, v75, v151
	v_add_u32_e32 v167, 0x42, v73
	v_cndmask_b32_e32 v153, v208, v207, vcc
	v_subrev_u32_e32 v201, 47, v74
	v_cmp_gt_i32_e32 vcc, 0, v75
	v_mul_f32_e32 v214, v214, v215
	v_cvt_f32_u32_e32 v151, v151
	v_cndmask_b32_e32 v167, v201, v167, vcc
	v_exp_f32_e32 v214, v214
	v_cvt_f32_u32_e32 v167, v167
	v_mul_f32_e32 v151, v153, v151
	v_cndmask_b32_e32 v153, v208, v207, vcc
	v_mul_f32_e32 v213, v214, v213
	v_mul_f32_e32 v153, v153, v167
	v_add_u32_e32 v167, 0x41, v73
	v_subrev_u32_e32 v201, 46, v74
	v_cmp_gt_i32_e32 vcc, -1, v75
	s_nop 0
	v_cvt_pk_bf16_f32 v213, v209, v213
	v_add_u32_e32 v209, 64, v73
	v_subrev_u32_e32 v74, 45, v74
	v_cndmask_b32_e32 v167, v201, v167, vcc
	v_cndmask_b32_e32 v201, v208, v207, vcc
	v_cmp_gt_i32_e32 vcc, -2, v75
	v_cvt_f32_u32_e32 v167, v167
	v_exp_f32_e32 v151, v151
	v_cndmask_b32_e32 v74, v74, v209, vcc
	v_cvt_f32_u32_e32 v74, v74
	v_mul_f32_e32 v167, v201, v167
	v_cndmask_b32_e32 v201, v208, v207, vcc
	v_cmp_gt_i32_e32 vcc, -15, v75
	v_mul_f32_e32 v74, v201, v74
	v_exp_f32_e32 v74, v74
	v_mul_f32_e32 v48, v151, v48
	v_exp_f32_e32 v153, v153
	v_mfma_f32_16x16x32_bf16 v[44:47], v[44:47], v[24:27], 0
	v_mul_f32_e32 v51, v74, v51
	v_add_u32_e32 v74, 51, v73
	v_cndmask_b32_e32 v74, v149, v74, vcc
	v_cndmask_b32_e32 v149, v208, v207, vcc
	v_cmp_gt_i32_e32 vcc, -16, v75
	v_cvt_f32_u32_e32 v74, v74
	v_mul_f32_e32 v49, v153, v49
	v_cndmask_b32_e32 v151, v162, v155, vcc
	v_cvt_f32_u32_e32 v151, v151
	v_mul_f32_e32 v74, v149, v74
	v_cndmask_b32_e32 v149, v208, v207, vcc
	v_cmp_gt_i32_e32 vcc, s80, v75
	v_mul_f32_e32 v149, v149, v151
	v_exp_f32_e32 v167, v167
	v_cndmask_b32_e32 v151, v200, v163, vcc
	v_cndmask_b32_e32 v153, v208, v207, vcc
	v_cmp_gt_i32_e32 vcc, s81, v75
	v_cvt_f32_u32_e32 v151, v151
	v_exp_f32_e32 v74, v74
	v_cndmask_b32_e32 v75, v220, v217, vcc
	v_cvt_f32_u32_e32 v75, v75
	v_mul_f32_e32 v151, v153, v151
	v_cndmask_b32_e32 v153, v208, v207, vcc
	v_exp_f32_e32 v149, v149
	v_mul_f32_e32 v75, v153, v75
	v_exp_f32_e32 v75, v75
	v_exp_f32_e32 v151, v151
	v_mfma_f32_16x16x32_bf16 v[84:87], v[56:59], v[210:213], v[84:87]
	v_mul_f32_e32 v50, v167, v50
	v_mul_f32_e32 v47, v75, v47
	v_mul_f32_e32 v74, v74, v44
	v_mfma_f32_16x16x32_bf16 v[80:83], v[52:55], v[210:213], v[80:83]
	v_mul_f32_e32 v149, v149, v45
	v_mul_f32_e32 v151, v151, v46
	s_nop 0
	v_cvt_pk_bf16_f32 v44, v48, v49
	v_mfma_f32_16x16x32_bf16 v[92:95], v[60:63], v[210:213], v[92:95]
	s_nop 0
	v_cvt_pk_bf16_f32 v45, v50, v51
	s_nop 0
	v_cvt_pk_bf16_f32 v46, v74, v149
	s_nop 0
	v_cvt_pk_bf16_f32 v47, v151, v47
	v_mfma_f32_16x16x32_bf16 v[88:91], v[64:67], v[210:213], v[88:91]
	v_subrev_u32_e32 v73, 32, v73
	v_lshl_add_u64 v[70:71], v[70:71], 0, s[72:73]
	s_cmpk_eq_i32 s0, 0x80
	v_mfma_f32_16x16x32_bf16 v[40:43], v[56:59], v[44:47], v[40:43]
	v_lshl_add_u64 v[68:69], v[68:69], 0, s[72:73]
	v_mfma_f32_16x16x32_bf16 v[36:39], v[52:55], v[44:47], v[36:39]
	v_mfma_f32_16x16x32_bf16 v[32:35], v[60:63], v[44:47], v[32:35]
	v_mfma_f32_16x16x32_bf16 v[28:31], v[64:67], v[44:47], v[28:31]
	s_cbranch_scc0 .LBB0_726
; __device__ __forceinline__ float shx(float v, int mask, int lane) { return __builtin_bit_cast(float, __builtin_amdgcn_ds_bpermute((lane ^ mask) << 2, __builtin_bit_cast(int, v))); }
; __device__ __forceinline__ unsigned pk2(float lo, float hi) { return pg8::cvt_pk_bf16(lo, hi); }
; __device__ __forceinline__ float ex2(float x) { return __builtin_amdgcn_exp2f(x); }
; #define MFMA16(a, b, c) __builtin_amdgcn_mfma_f32_16x16x32_bf16(a, b, c, 0, 0, 0)
; __device__ __forceinline__ void ret_output(Frame& F, const Trunk& T, int layer) {
;     ...
;         bf16x8 rf[4], rb[4];
; #pragma unroll
;         for (int nn = 0; nn < 4; ++nn) { const size_t oo = ((size_t)(gch * 8 + h) * 64 + 16 * nn + i16) * 32 + quad * 8;
;             const f32x4 a0 = *(const f32x4*)(kvf + oo), a1 = *(const f32x4*)(kvf + oo + 4), b0 = *(const f32x4*)(kvb + oo), b1 = *(const f32x4*)(kvb + oo + 4);
;             const u32x4 wa = {pk2(a0[0], a0[1]), pk2(a0[2], a0[3]), pk2(a1[0], a1[1]), pk2(a1[2], a1[3])}, wb = {pk2(b0[0], b0[1]), pk2(b0[2], b0[3]), pk2(b1[0], b1[1]), pk2(b1[2], b1[3])};
;             rf[nn] = __builtin_bit_cast(bf16x8, wa); rb[nn] = __builtin_bit_cast(bf16x8, wb); }
; #pragma unroll
;         for (int qt = 0; qt < 4; ++qt) {
;             const int tau = 64 * half + 16 * qt + i16; const size_t qrow = row0 + tau;
;             const float wqf = ex2(lgf * (float)(tau + 1)), wqb = ex2(lgb * (float)(128 - tau));
;             float s1 = 0.f;
; #pragma unroll
;             for (int nn = 0; nn < 4; ++nn) { const f32x4 xf = MFMA16(rf[nn], qf[qt], z4), xb = MFMA16(rb[nn], qf[qt], z4); o[qt][nn] = o[qt][nn] + xf * wqf + xb * wqb; s1 += (o[qt][nn][0] + o[qt][nn][1]) + (o[qt][nn][2] + o[qt][nn][3]); }
;             s1 += shx(s1, 16, lane); s1 += shx(s1, 32, lane); const float mu = s1 * (1.f / 64.f); float s2 = 0.f;
	global_load_dwordx4 v[46:49], v[180:181], off offset:16
	global_load_dwordx4 v[50:53], v[180:181], off
	global_load_dwordx4 v[54:57], v[182:183], off offset:16
	global_load_dwordx4 v[58:61], v[182:183], off
	v_add_u32_e32 v151, 1, v147
	v_cvt_f32_u32_e32 v151, v151
	v_or_b32_e32 v210, 16, v147
	v_or_b32_e32 v209, 32, v147
	v_or_b32_e32 v149, 48, v147
	v_mul_f32_e32 v151, v207, v151
	v_exp_f32_e32 v162, v151
	v_sub_u32_e32 v151, 0x80, v147
	v_cvt_f32_ubyte0_e32 v151, v151
	v_mul_f32_e32 v151, v208, v151
	s_mov_b32 s5, 64
	s_waitcnt vmcnt(2)
	s_nop 0
	v_cvt_pk_bf16_f32 v44, v50, v51
	s_nop 0
	v_cvt_pk_bf16_f32 v45, v52, v53
	s_nop 0
	v_cvt_pk_bf16_f32 v46, v46, v47
	s_nop 0
	v_cvt_pk_bf16_f32 v47, v48, v49
	s_waitcnt vmcnt(0)
	s_nop 0
	v_cvt_pk_bf16_f32 v48, v58, v59
	s_nop 0
	v_cvt_pk_bf16_f32 v49, v60, v61
	s_nop 0
	v_cvt_pk_bf16_f32 v50, v54, v55
	s_nop 0
	v_cvt_pk_bf16_f32 v51, v56, v57
	global_load_dwordx4 v[54:57], v[184:185], off offset:16
	global_load_dwordx4 v[58:61], v[184:185], off
	global_load_dwordx4 v[62:65], v[186:187], off offset:16
	global_load_dwordx4 v[66:69], v[186:187], off
	s_waitcnt vmcnt(2)
	s_nop 0
	v_cvt_pk_bf16_f32 v52, v58, v59
	s_nop 0
	v_cvt_pk_bf16_f32 v53, v60, v61
	s_nop 0
	v_cvt_pk_bf16_f32 v54, v54, v55
	s_nop 0
	v_cvt_pk_bf16_f32 v55, v56, v57
	s_waitcnt vmcnt(0)
	s_nop 0
	v_cvt_pk_bf16_f32 v56, v66, v67
	s_nop 0
	v_cvt_pk_bf16_f32 v57, v68, v69
	s_nop 0
	v_cvt_pk_bf16_f32 v58, v62, v63
	s_nop 0
	v_cvt_pk_bf16_f32 v59, v64, v65
	global_load_dwordx4 v[62:65], v[188:189], off offset:16
	global_load_dwordx4 v[66:69], v[188:189], off
	global_load_dwordx4 v[70:73], v[190:191], off offset:16
	global_load_dwordx4 v[212:215], v[190:191], off
	s_waitcnt vmcnt(2)
	s_nop 0
	v_cvt_pk_bf16_f32 v60, v66, v67
	s_nop 0
	v_cvt_pk_bf16_f32 v61, v68, v69
	s_nop 0
	v_cvt_pk_bf16_f32 v62, v62, v63
	s_nop 0
	v_cvt_pk_bf16_f32 v63, v64, v65
	s_waitcnt vmcnt(0)
	s_nop 0
	v_cvt_pk_bf16_f32 v64, v212, v213
	s_nop 0
	v_cvt_pk_bf16_f32 v65, v214, v215
	s_nop 0
	v_cvt_pk_bf16_f32 v66, v70, v71
	s_nop 0
	v_cvt_pk_bf16_f32 v67, v72, v73
	global_load_dwordx4 v[70:73], v[192:193], off offset:16
	global_load_dwordx4 v[212:215], v[192:193], off
	global_load_dwordx4 v[216:219], v[194:195], off offset:16
	global_load_dwordx4 v[220:223], v[194:195], off
	s_waitcnt vmcnt(2)
	s_nop 0
	v_cvt_pk_bf16_f32 v68, v212, v213
	s_nop 0
	v_cvt_pk_bf16_f32 v69, v214, v215
	v_mfma_f32_16x16x32_bf16 v[212:215], v[44:47], v[116:119], 0
	s_nop 0
	v_cvt_pk_bf16_f32 v70, v70, v71
	s_nop 0
	v_cvt_pk_bf16_f32 v71, v72, v73
	s_waitcnt vmcnt(0)
	s_nop 0
	v_cvt_pk_bf16_f32 v72, v220, v221
	s_nop 0
	v_cvt_pk_bf16_f32 v73, v222, v223
	s_nop 0
	v_cvt_pk_bf16_f32 v74, v216, v217
	s_nop 0
	v_cvt_pk_bf16_f32 v75, v218, v219
	v_exp_f32_e32 v220, v151
	v_mfma_f32_16x16x32_bf16 v[216:219], v[48:51], v[116:119], 0
	s_nop 4
	v_fma_f32 v134, v162, v214, v134
	v_fma_f32 v135, v162, v215, v135
	v_pk_fma_f32 v[132:133], v[162:163], v[212:213], v[132:133] op_sel_hi:[0,1,1]
	v_pk_fma_f32 v[200:201], v[220:221], v[218:219], v[134:135] op_sel_hi:[0,1,1]
	v_pk_fma_f32 v[134:135], v[220:221], v[216:217], v[132:133] op_sel_hi:[0,1,1]
	v_pk_mov_b32 v[132:133], v[134:135], v[200:201] op_sel:[1,0]
	v_mov_b32_e32 v212, v134
	v_mov_b32_e32 v213, v201
	v_pk_add_f32 v[132:133], v[132:133], v[212:213]
	v_mfma_f32_16x16x32_bf16 v[212:215], v[52:55], v[116:119], 0
	v_add_f32_e32 v132, v132, v133
	v_add_f32_e32 v132, 0, v132
	v_mfma_f32_16x16x32_bf16 v[216:219], v[56:59], v[116:119], 0
	s_nop 4
	v_fma_f32 v130, v162, v214, v130
	v_fma_f32 v131, v162, v215, v131
	v_pk_fma_f32 v[128:129], v[162:163], v[212:213], v[128:129] op_sel_hi:[0,1,1]
	v_pk_fma_f32 v[130:131], v[220:221], v[218:219], v[130:131] op_sel_hi:[0,1,1]
	v_pk_fma_f32 v[128:129], v[220:221], v[216:217], v[128:129] op_sel_hi:[0,1,1]
	v_pk_mov_b32 v[212:213], v[128:129], v[130:131] op_sel:[1,0]
	v_mov_b32_e32 v214, v128
	v_mov_b32_e32 v215, v131
	v_pk_add_f32 v[212:213], v[212:213], v[214:215]
	v_mfma_f32_16x16x32_bf16 v[216:219], v[64:67], v[116:119], 0
	v_add_f32_e64 v222, v212, v213
	v_add_f32_e64 v223, v213, v212
	v_mfma_f32_16x16x32_bf16 v[212:215], v[60:63], v[116:119], 0
	s_nop 7
	v_pk_fma_f32 v[126:127], v[162:163], v[214:215], v[126:127] op_sel_hi:[0,1,1]
	v_pk_fma_f32 v[124:125], v[162:163], v[212:213], v[124:125] op_sel_hi:[0,1,1]
	v_mfma_f32_16x16x32_bf16 v[212:215], v[68:71], v[116:119], 0
	v_fma_f32 v126, v220, v218, v126
	v_fma_f32 v127, v220, v219, v127
	v_pk_fma_f32 v[124:125], v[220:221], v[216:217], v[124:125] op_sel_hi:[0,1,1]
	v_add_f32_e32 v216, v124, v125
	v_mfma_f32_16x16x32_bf16 v[116:119], v[72:75], v[116:119], 0
	v_add_f32_e32 v218, v126, v127
	s_nop 1
	v_pk_fma_f32 v[122:123], v[162:163], v[214:215], v[122:123] op_sel_hi:[0,1,1]
	v_pk_fma_f32 v[120:121], v[162:163], v[212:213], v[120:121] op_sel_hi:[0,1,1]
	s_nop 2
	v_pk_fma_f32 v[118:119], v[220:221], v[118:119], v[122:123] op_sel_hi:[0,1,1]
	v_pk_fma_f32 v[116:117], v[220:221], v[116:117], v[120:121] op_sel_hi:[0,1,1]
	v_mov_b32_e32 v133, v116
	v_mov_b32_e32 v223, v117
	v_mov_b32_e32 v217, v118
	v_mov_b32_e32 v219, v119
	v_pk_add_f32 v[120:121], v[132:133], v[222:223]
	v_pk_add_f32 v[122:123], v[216:217], v[218:219]
	s_nop 0
	v_pk_add_f32 v[120:121], v[120:121], v[122:123]
	s_nop 0
	v_add_f32_e32 v120, v120, v121
	ds_bpermute_b32 v121, v161, v120
	s_waitcnt lgkmcnt(0)
	v_add_f32_e32 v120, v120, v121
	ds_bpermute_b32 v121, v202, v120
	s_waitcnt lgkmcnt(0)
; __device__ __forceinline__ float shx(float v, int mask, int lane) { return __builtin_bit_cast(float, __builtin_amdgcn_ds_bpermute((lane ^ mask) << 2, __builtin_bit_cast(int, v))); }
; __device__ __forceinline__ float silu_mul(float g, float u) { return g * u * __builtin_amdgcn_rcpf(1.0f + __expf(-g)); }
; __device__ __forceinline__ unsigned pk2(float lo, float hi) { return pg8::cvt_pk_bf16(lo, hi); }
; __device__ __forceinline__ void ret_output(Frame& F, const Trunk& T, int layer) {
;     ...
;             s1 += shx(s1, 16, lane); s1 += shx(s1, 32, lane); const float mu = s1 * (1.f / 64.f); float s2 = 0.f;
; #pragma unroll
;             for (int nn = 0; nn < 4; ++nn) { o[qt][nn] = o[qt][nn] - mu; s2 += (o[qt][nn][0] * o[qt][nn][0] + o[qt][nn][1] * o[qt][nn][1]) + (o[qt][nn][2] * o[qt][nn][2] + o[qt][nn][3] * o[qt][nn][3]); }
;             s2 += shx(s2, 16, lane); s2 += shx(s2, 32, lane); const float rs = rsqrtf(s2 * (1.f / 64.f) + 1e-5f);
; #pragma unroll
;             for (int nn = 0; nn < 4; ++nn) { const int col = h * 64 + 16 * nn + 4 * quad; const u32x2 gw = *(const u32x2*)(proj + qrow * NIN + C_GR + col);
;                 const float g0 = __uint_as_float(gw.x << 16), g1 = __uint_as_float(gw.x & 0xffff0000u), g2 = __uint_as_float(gw.y << 16), g3 = __uint_as_float(gw.y & 0xffff0000u);
;                 const f32x4 v = o[qt][nn] * rs; u32x2 w; w.x = pk2(pg8::silu_mul(g0, v[0]), pg8::silu_mul(g1, v[1])); w.y = pk2(pg8::silu_mul(g2, v[2]), pg8::silu_mul(g3, v[3]));
;                 *(u32x2*)(mix + qrow * DM + MX_R + col) = w; }
	v_add_f32_e32 v151, v120, v121
	v_fmamk_f32 v135, v151, 0xbc800000, v135
	v_fmac_f32_e32 v134, 0xbc800000, v151
	v_fmamk_f32 v201, v151, 0xbc800000, v201
	v_fmac_f32_e32 v200, 0xbc800000, v151
	v_pk_mul_f32 v[120:121], v[200:201], v[200:201]
	v_pk_mul_f32 v[122:123], v[134:135], v[134:135]
	v_fmamk_f32 v129, v151, 0xbc800000, v129
	v_pk_mov_b32 v[132:133], v[122:123], v[120:121] op_sel:[1,0]
	v_mov_b32_e32 v123, v121
	v_pk_add_f32 v[120:121], v[132:133], v[122:123]
	v_fmac_f32_e32 v128, 0xbc800000, v151
	v_fmamk_f32 v131, v151, 0xbc800000, v131
	v_fmac_f32_e32 v130, 0xbc800000, v151
	v_pk_add_f32 v[120:121], v[120:121], v[120:121] op_sel_hi:[0,1]
	v_pk_mul_f32 v[122:123], v[130:131], v[130:131]
	v_pk_mul_f32 v[132:133], v[128:129], v[128:129]
	v_fmac_f32_e32 v124, 0xbc800000, v151
	v_pk_mov_b32 v[162:163], v[132:133], v[122:123] op_sel:[1,0]
	v_mov_b32_e32 v133, v123
	v_fmamk_f32 v125, v151, 0xbc800000, v125
	v_fmac_f32_e32 v126, 0xbc800000, v151
	v_mul_f32_e32 v120, v124, v124
	v_pk_add_f32 v[122:123], v[162:163], v[132:133]
	v_fmamk_f32 v127, v151, 0xbc800000, v127
	v_pk_fma_f32 v[132:133], v[124:125], v[124:125], v[120:121] op_sel_hi:[1,1,0]
	v_mul_f32_e32 v120, v126, v126
	v_pk_add_f32 v[122:123], v[122:123], v[122:123] op_sel_hi:[0,1]
	v_pk_fma_f32 v[162:163], v[126:127], v[126:127], v[120:121] op_sel_hi:[1,1,0]
	v_fmamk_f32 v119, v151, 0xbc800000, v119
	v_fmac_f32_e32 v118, 0xbc800000, v151
	v_fmamk_f32 v117, v151, 0xbc800000, v117
	v_fmac_f32_e32 v116, 0xbc800000, v151
	v_mul_f32_e32 v132, v116, v116
	v_mul_f32_e32 v162, v117, v117
	v_mul_f32_e32 v120, v118, v118
	v_mul_f32_e32 v122, v119, v119
	v_pk_add_f32 v[132:133], v[132:133], v[162:163]
	v_pk_add_f32 v[120:121], v[120:121], v[122:123]
	v_mov_b32_e32 v151, v157
	v_pk_add_f32 v[120:121], v[132:133], v[120:121]
	v_lshl_add_u64 v[132:133], v[198:199], 0, s[76:77]
	v_lshl_add_u64 v[162:163], v[132:133], 0, v[150:151]
	global_load_dwordx2 v[224:225], v[162:163], off offset:32
	global_load_dwordx2 v[226:227], v[162:163], off offset:64
	global_load_dwordx2 v[228:229], v[162:163], off offset:96
	global_load_dwordx2 v[162:163], v[162:163], off
	v_add_f32_e32 v120, v120, v121
	ds_bpermute_b32 v121, v161, v120
	v_lshlrev_b64 v[122:123], 12, v[196:197]
	v_lshl_add_u64 v[122:123], s[6:7], 0, v[122:123]
	v_lshl_add_u64 v[122:123], v[122:123], 0, s[78:79]
	s_waitcnt lgkmcnt(0)
	v_add_f32_e32 v120, v120, v121
	ds_bpermute_b32 v121, v202, v120
	s_waitcnt lgkmcnt(0)
	v_add_f32_e32 v120, v120, v121
	v_fmamk_f32 v120, v120, 0x3c800000, v232
	v_cmp_gt_f32_e32 vcc, s96, v120
	v_mul_f32_e32 v121, 0x4b800000, v120
	s_waitcnt vmcnt(0)
	v_and_b32_e32 v153, 0xffff0000, v162
	v_cndmask_b32_e32 v120, v120, v121, vcc
	v_rsq_f32_e32 v120, v120
	v_lshlrev_b32_e32 v155, 16, v163
	v_and_b32_e32 v167, 0xffff0000, v163
	v_mul_f32_e32 v121, 0x45800000, v120
	v_cndmask_b32_e32 v120, v120, v121, vcc
	v_lshlrev_b32_e32 v121, 16, v162
	v_pk_mul_f32 v[134:135], v[134:135], v[120:121] op_sel_hi:[1,0]
	v_pk_mul_f32 v[162:163], v[200:201], v[120:121] op_sel_hi:[1,0]
	v_mul_f32_e32 v134, v134, v121
	v_mul_f32_e32 v121, 0xbfb8aa3b, v121
	v_exp_f32_e32 v121, v121
	s_nop 0
	v_add_f32_e32 v121, 1.0, v121
	v_rcp_f32_e32 v121, v121
	s_nop 0
	v_mul_f32_e32 v121, v121, v134
	v_mul_f32_e32 v134, v135, v153
	v_mul_f32_e32 v135, 0xbfb8aa3b, v153
	v_exp_f32_e32 v135, v135
	v_mul_f32_e32 v153, 0xbfb8aa3b, v167
	v_exp_f32_e32 v153, v153
	v_add_f32_e32 v135, 1.0, v135
	v_rcp_f32_e32 v135, v135
	v_add_f32_e32 v153, 1.0, v153
	v_rcp_f32_e32 v153, v153
	v_mul_f32_e32 v134, v135, v134
	v_mul_f32_e32 v135, 0xbfb8aa3b, v155
	v_exp_f32_e32 v135, v135
	s_nop 0
	v_cvt_pk_bf16_f32 v134, v121, v134
	v_mul_f32_e32 v121, v162, v155
	v_add_f32_e32 v135, 1.0, v135
	v_rcp_f32_e32 v135, v135
	s_nop 0
	v_mul_f32_e32 v121, v135, v121
	v_mul_f32_e32 v135, v163, v167
	v_mul_f32_e32 v135, v153, v135
	s_nop 0
	v_cvt_pk_bf16_f32 v135, v121, v135
	v_lshl_add_u64 v[162:163], v[122:123], 0, v[150:151]
	v_mov_b32_e32 v153, v157
	global_store_dwordx2 v[162:163], v[134:135], off
	v_mov_b32_e32 v167, v157
	s_waitcnt vmcnt(1)
	v_lshlrev_b32_e32 v121, 16, v224
	v_pk_mul_f32 v[128:129], v[128:129], v[120:121] op_sel_hi:[1,0]
	v_pk_mul_f32 v[130:131], v[130:131], v[120:121] op_sel_hi:[1,0]
	v_mul_f32_e32 v128, v128, v121
	v_mul_f32_e32 v121, 0xbfb8aa3b, v121
	v_exp_f32_e32 v121, v121
	v_and_b32_e32 v134, 0xffff0000, v224
	v_lshlrev_b32_e32 v155, 16, v225
	v_and_b32_e32 v135, 0xffff0000, v225
	v_add_f32_e32 v121, 1.0, v121
	v_rcp_f32_e32 v121, v121
	s_nop 0
	v_mul_f32_e32 v121, v121, v128
	v_mul_f32_e32 v128, v129, v134
	v_mul_f32_e32 v129, 0xbfb8aa3b, v134
	v_exp_f32_e32 v129, v129
	s_nop 0
	v_add_f32_e32 v129, 1.0, v129
	v_rcp_f32_e32 v129, v129
	s_nop 0
	v_mul_f32_e32 v128, v129, v128
	v_mul_f32_e32 v129, 0xbfb8aa3b, v155
	s_nop 0
	v_cvt_pk_bf16_f32 v128, v121, v128
	v_mul_f32_e32 v121, v130, v155
	v_exp_f32_e32 v129, v129
	v_mul_f32_e32 v130, 0xbfb8aa3b, v135
	v_exp_f32_e32 v130, v130
	v_mov_b32_e32 v155, v157
	v_add_f32_e32 v129, 1.0, v129
	v_rcp_f32_e32 v129, v129
	v_add_f32_e32 v130, 1.0, v130
	v_rcp_f32_e32 v130, v130
	v_mul_f32_e32 v121, v129, v121
	v_mul_f32_e32 v129, v131, v135
	v_mul_f32_e32 v129, v130, v129
	s_nop 0
	v_cvt_pk_bf16_f32 v129, v121, v129
	v_lshl_add_u64 v[130:131], v[122:123], 0, v[152:153]
	global_store_dwordx2 v[130:131], v[128:129], off
	s_waitcnt vmcnt(2)
; __device__ __forceinline__ float shx(float v, int mask, int lane) { return __builtin_bit_cast(float, __builtin_amdgcn_ds_bpermute((lane ^ mask) << 2, __builtin_bit_cast(int, v))); }
; __device__ __forceinline__ float silu_mul(float g, float u) { return g * u * __builtin_amdgcn_rcpf(1.0f + __expf(-g)); }
; __device__ __forceinline__ unsigned pk2(float lo, float hi) { return pg8::cvt_pk_bf16(lo, hi); }
; __device__ __forceinline__ float ex2(float x) { return __builtin_amdgcn_exp2f(x); }
; #define MFMA16(a, b, c) __builtin_amdgcn_mfma_f32_16x16x32_bf16(a, b, c, 0, 0, 0)
; __device__ __forceinline__ void ret_output(Frame& F, const Trunk& T, int layer) {
;     ...
;         for (int qt = 0; qt < 4; ++qt) {
;             const int tau = 64 * half + 16 * qt + i16; const size_t qrow = row0 + tau;
;             const float wqf = ex2(lgf * (float)(tau + 1)), wqb = ex2(lgb * (float)(128 - tau));
;             float s1 = 0.f;
; #pragma unroll
;             for (int nn = 0; nn < 4; ++nn) { const f32x4 xf = MFMA16(rf[nn], qf[qt], z4), xb = MFMA16(rb[nn], qf[qt], z4); o[qt][nn] = o[qt][nn] + xf * wqf + xb * wqb; s1 += (o[qt][nn][0] + o[qt][nn][1]) + (o[qt][nn][2] + o[qt][nn][3]); }
;             s1 += shx(s1, 16, lane); s1 += shx(s1, 32, lane); const float mu = s1 * (1.f / 64.f); float s2 = 0.f;
;     ...
;             for (int nn = 0; nn < 4; ++nn) { const int col = h * 64 + 16 * nn + 4 * quad; const u32x2 gw = *(const u32x2*)(proj + qrow * NIN + C_GR + col);
;                 const float g0 = __uint_as_float(gw.x << 16), g1 = __uint_as_float(gw.x & 0xffff0000u), g2 = __uint_as_float(gw.y << 16), g3 = __uint_as_float(gw.y & 0xffff0000u);
;                 const f32x4 v = o[qt][nn] * rs; u32x2 w; w.x = pk2(pg8::silu_mul(g0, v[0]), pg8::silu_mul(g1, v[1])); w.y = pk2(pg8::silu_mul(g2, v[2]), pg8::silu_mul(g3, v[3]));
;                 *(u32x2*)(mix + qrow * DM + MX_R + col) = w; }
	v_lshlrev_b32_e32 v121, 16, v226
	v_pk_mul_f32 v[124:125], v[124:125], v[120:121] op_sel_hi:[1,0]
	v_pk_mul_f32 v[126:127], v[126:127], v[120:121] op_sel_hi:[1,0]
	v_mul_f32_e32 v124, v124, v121
	v_mul_f32_e32 v121, 0xbfb8aa3b, v121
	v_exp_f32_e32 v121, v121
	v_and_b32_e32 v128, 0xffff0000, v226
	v_lshlrev_b32_e32 v130, 16, v227
	v_and_b32_e32 v129, 0xffff0000, v227
	v_add_f32_e32 v121, 1.0, v121
	v_rcp_f32_e32 v121, v121
	s_nop 0
	v_mul_f32_e32 v121, v121, v124
	v_mul_f32_e32 v124, v125, v128
	v_mul_f32_e32 v125, 0xbfb8aa3b, v128
	v_exp_f32_e32 v125, v125
	s_nop 0
	v_add_f32_e32 v125, 1.0, v125
	v_rcp_f32_e32 v125, v125
	s_nop 0
	v_mul_f32_e32 v124, v125, v124
	v_mul_f32_e32 v125, 0xbfb8aa3b, v130
	s_nop 0
	v_cvt_pk_bf16_f32 v124, v121, v124
	v_mul_f32_e32 v121, v126, v130
	v_exp_f32_e32 v125, v125
	v_mul_f32_e32 v126, 0xbfb8aa3b, v129
	v_exp_f32_e32 v126, v126
	v_add_f32_e32 v125, 1.0, v125
	v_rcp_f32_e32 v125, v125
	v_add_f32_e32 v126, 1.0, v126
	v_rcp_f32_e32 v126, v126
	v_mul_f32_e32 v121, v125, v121
	v_mul_f32_e32 v125, v127, v129
	v_mul_f32_e32 v125, v126, v125
	s_nop 0
	v_cvt_pk_bf16_f32 v125, v121, v125
	v_lshl_add_u64 v[126:127], v[122:123], 0, v[154:155]
	global_store_dwordx2 v[126:127], v[124:125], off
	s_waitcnt vmcnt(3)
	v_lshlrev_b32_e32 v121, 16, v228
	v_pk_mul_f32 v[118:119], v[118:119], v[120:121] op_sel_hi:[1,0]
	v_pk_mul_f32 v[116:117], v[116:117], v[120:121] op_sel_hi:[1,0]
	v_mul_f32_e32 v120, 0xbfb8aa3b, v121
	v_exp_f32_e32 v120, v120
	v_and_b32_e32 v124, 0xffff0000, v228
	v_mul_f32_e32 v116, v116, v121
	v_mul_f32_e32 v117, v117, v124
	v_add_f32_e32 v120, 1.0, v120
	v_rcp_f32_e32 v120, v120
	v_lshlrev_b32_e32 v126, 16, v229
	v_and_b32_e32 v125, 0xffff0000, v229
	v_mul_f32_e32 v116, v120, v116
	v_mul_f32_e32 v120, 0xbfb8aa3b, v124
	v_exp_f32_e32 v120, v120
	s_nop 0
	v_add_f32_e32 v120, 1.0, v120
	v_rcp_f32_e32 v120, v120
	s_nop 0
	v_mul_f32_e32 v117, v120, v117
	s_nop 0
	v_cvt_pk_bf16_f32 v116, v116, v117
	v_mul_f32_e32 v117, v118, v126
	v_mul_f32_e32 v118, 0xbfb8aa3b, v126
	v_exp_f32_e32 v118, v118
	s_nop 0
	v_add_f32_e32 v118, 1.0, v118
	v_rcp_f32_e32 v118, v118
	s_nop 0
	v_mul_f32_e32 v117, v118, v117
	v_mul_f32_e32 v118, v119, v125
	v_mul_f32_e32 v119, 0xbfb8aa3b, v125
	v_exp_f32_e32 v119, v119
	s_nop 0
	v_add_f32_e32 v119, 1.0, v119
	v_rcp_f32_e32 v119, v119
	s_nop 0
	v_mul_f32_e32 v118, v119, v118
	s_nop 0
	v_cvt_pk_bf16_f32 v117, v117, v118
	v_lshl_add_u64 v[118:119], v[122:123], 0, v[166:167]
	global_store_dwordx2 v[118:119], v[116:117], off
	v_add_u32_e32 v116, 17, v147
	v_cvt_f32_u32_e32 v116, v116
	v_mfma_f32_16x16x32_bf16 v[122:125], v[48:51], v[96:99], 0
	v_mul_f32_e32 v116, v207, v116
	v_exp_f32_e32 v126, v116
	v_sub_u32_e32 v116, 0x80, v210
	v_cvt_f32_ubyte0_e32 v116, v116
	v_mul_f32_e32 v116, v208, v116
	v_exp_f32_e32 v128, v116
	v_mfma_f32_16x16x32_bf16 v[116:119], v[44:47], v[96:99], 0
	s_nop 7
	v_pk_fma_f32 v[114:115], v[126:127], v[118:119], v[114:115] op_sel_hi:[0,1,1]
	v_pk_fma_f32 v[112:113], v[126:127], v[116:117], v[112:113] op_sel_hi:[0,1,1]
	v_pk_fma_f32 v[120:121], v[128:129], v[124:125], v[114:115] op_sel_hi:[0,1,1]
	v_pk_fma_f32 v[118:119], v[128:129], v[122:123], v[112:113] op_sel_hi:[0,1,1]
	v_pk_mov_b32 v[112:113], v[118:119], v[120:121] op_sel:[1,0]
	v_mov_b32_e32 v114, v118
	v_mov_b32_e32 v115, v121
	v_pk_add_f32 v[112:113], v[112:113], v[114:115]
	v_mfma_f32_16x16x32_bf16 v[122:125], v[56:59], v[96:99], 0
	v_add_f32_e32 v112, v112, v113
	v_add_f32_e32 v116, 0, v112
	v_mfma_f32_16x16x32_bf16 v[112:115], v[52:55], v[96:99], 0
	s_nop 7
	v_pk_fma_f32 v[110:111], v[126:127], v[114:115], v[110:111] op_sel_hi:[0,1,1]
	v_pk_fma_f32 v[108:109], v[126:127], v[112:113], v[108:109] op_sel_hi:[0,1,1]
	v_pk_fma_f32 v[114:115], v[128:129], v[124:125], v[110:111] op_sel_hi:[0,1,1]
	v_pk_fma_f32 v[112:113], v[128:129], v[122:123], v[108:109] op_sel_hi:[0,1,1]
	v_pk_mov_b32 v[108:109], v[112:113], v[114:115] op_sel:[1,0]
	v_mov_b32_e32 v110, v112
	v_mov_b32_e32 v111, v115
	v_pk_add_f32 v[108:109], v[108:109], v[110:111]
	v_mfma_f32_16x16x32_bf16 v[122:125], v[64:67], v[96:99], 0
	v_add_f32_e64 v130, v108, v109
	v_add_f32_e64 v131, v109, v108
	v_mfma_f32_16x16x32_bf16 v[108:111], v[60:63], v[96:99], 0
	s_nop 7
	v_pk_fma_f32 v[106:107], v[126:127], v[110:111], v[106:107] op_sel_hi:[0,1,1]
	v_pk_fma_f32 v[104:105], v[126:127], v[108:109], v[104:105] op_sel_hi:[0,1,1]
	v_pk_fma_f32 v[108:109], v[128:129], v[124:125], v[106:107] op_sel_hi:[0,1,1]
	v_pk_fma_f32 v[106:107], v[128:129], v[122:123], v[104:105] op_sel_hi:[0,1,1]
	v_mfma_f32_16x16x32_bf16 v[122:125], v[68:71], v[96:99], 0
	v_add_f32_e32 v104, v106, v107
	v_add_f32_e32 v110, v108, v109
	v_mfma_f32_16x16x32_bf16 v[96:99], v[72:75], v[96:99], 0
	s_nop 4
	v_fma_f32 v102, v126, v124, v102
	v_fma_f32 v103, v126, v125, v103
	v_pk_fma_f32 v[100:101], v[126:127], v[122:123], v[100:101] op_sel_hi:[0,1,1]
	v_pk_fma_f32 v[102:103], v[128:129], v[98:99], v[102:103] op_sel_hi:[0,1,1]
	v_pk_fma_f32 v[100:101], v[128:129], v[96:97], v[100:101] op_sel_hi:[0,1,1]
	v_mov_b32_e32 v117, v100
	v_mov_b32_e32 v131, v101
	v_mov_b32_e32 v105, v102
	v_mov_b32_e32 v111, v103
	v_pk_add_f32 v[96:97], v[116:117], v[130:131]
	v_pk_add_f32 v[98:99], v[104:105], v[110:111]
	s_nop 0
	v_pk_add_f32 v[96:97], v[96:97], v[98:99]
	s_nop 0
	v_add_f32_e32 v96, v96, v97
	ds_bpermute_b32 v97, v161, v96
	s_waitcnt lgkmcnt(0)
	v_add_f32_e32 v96, v96, v97
	ds_bpermute_b32 v97, v202, v96
	s_waitcnt lgkmcnt(0)
; __device__ __forceinline__ float shx(float v, int mask, int lane) { return __builtin_bit_cast(float, __builtin_amdgcn_ds_bpermute((lane ^ mask) << 2, __builtin_bit_cast(int, v))); }
; __device__ __forceinline__ float silu_mul(float g, float u) { return g * u * __builtin_amdgcn_rcpf(1.0f + __expf(-g)); }
; __device__ __forceinline__ unsigned pk2(float lo, float hi) { return pg8::cvt_pk_bf16(lo, hi); }
; __device__ __forceinline__ void ret_output(Frame& F, const Trunk& T, int layer) {
;     ...
;             s1 += shx(s1, 16, lane); s1 += shx(s1, 32, lane); const float mu = s1 * (1.f / 64.f); float s2 = 0.f;
; #pragma unroll
;             for (int nn = 0; nn < 4; ++nn) { o[qt][nn] = o[qt][nn] - mu; s2 += (o[qt][nn][0] * o[qt][nn][0] + o[qt][nn][1] * o[qt][nn][1]) + (o[qt][nn][2] * o[qt][nn][2] + o[qt][nn][3] * o[qt][nn][3]); }
;             s2 += shx(s2, 16, lane); s2 += shx(s2, 32, lane); const float rs = rsqrtf(s2 * (1.f / 64.f) + 1e-5f);
; #pragma unroll
;             for (int nn = 0; nn < 4; ++nn) { const int col = h * 64 + 16 * nn + 4 * quad; const u32x2 gw = *(const u32x2*)(proj + qrow * NIN + C_GR + col);
;                 const float g0 = __uint_as_float(gw.x << 16), g1 = __uint_as_float(gw.x & 0xffff0000u), g2 = __uint_as_float(gw.y << 16), g3 = __uint_as_float(gw.y & 0xffff0000u);
;                 const f32x4 v = o[qt][nn] * rs; u32x2 w; w.x = pk2(pg8::silu_mul(g0, v[0]), pg8::silu_mul(g1, v[1])); w.y = pk2(pg8::silu_mul(g2, v[2]), pg8::silu_mul(g3, v[3]));
;                 *(u32x2*)(mix + qrow * DM + MX_R + col) = w; }
	v_add_f32_e32 v116, v96, v97
	v_fmamk_f32 v119, v116, 0xbc800000, v119
	v_fmac_f32_e32 v118, 0xbc800000, v116
	v_fmamk_f32 v121, v116, 0xbc800000, v121
	v_fmac_f32_e32 v120, 0xbc800000, v116
	v_pk_mul_f32 v[96:97], v[120:121], v[120:121]
	v_pk_mul_f32 v[98:99], v[118:119], v[118:119]
	v_fmamk_f32 v113, v116, 0xbc800000, v113
	v_pk_mov_b32 v[104:105], v[98:99], v[96:97] op_sel:[1,0]
	v_mov_b32_e32 v99, v97
	v_pk_add_f32 v[96:97], v[104:105], v[98:99]
	v_fmac_f32_e32 v112, 0xbc800000, v116
	v_fmamk_f32 v115, v116, 0xbc800000, v115
	v_fmac_f32_e32 v114, 0xbc800000, v116
	v_pk_add_f32 v[96:97], v[96:97], v[96:97] op_sel_hi:[0,1]
	v_pk_mul_f32 v[98:99], v[114:115], v[114:115]
	v_pk_mul_f32 v[104:105], v[112:113], v[112:113]
	v_fmac_f32_e32 v106, 0xbc800000, v116
	v_pk_mov_b32 v[110:111], v[104:105], v[98:99] op_sel:[1,0]
	v_mov_b32_e32 v105, v99
	v_fmamk_f32 v107, v116, 0xbc800000, v107
	v_fmac_f32_e32 v108, 0xbc800000, v116
	v_mul_f32_e32 v96, v106, v106
	v_pk_add_f32 v[98:99], v[110:111], v[104:105]
	v_fmamk_f32 v109, v116, 0xbc800000, v109
	v_pk_fma_f32 v[104:105], v[106:107], v[106:107], v[96:97] op_sel_hi:[1,1,0]
	v_mul_f32_e32 v96, v108, v108
	v_pk_add_f32 v[98:99], v[98:99], v[98:99] op_sel_hi:[0,1]
	v_pk_fma_f32 v[110:111], v[108:109], v[108:109], v[96:97] op_sel_hi:[1,1,0]
	v_fmamk_f32 v103, v116, 0xbc800000, v103
	v_fmac_f32_e32 v102, 0xbc800000, v116
	v_fmamk_f32 v101, v116, 0xbc800000, v101
	v_fmac_f32_e32 v100, 0xbc800000, v116
	v_mul_f32_e32 v104, v100, v100
	v_mul_f32_e32 v110, v101, v101
	v_mul_f32_e32 v96, v102, v102
	v_mul_f32_e32 v98, v103, v103
	v_pk_add_f32 v[104:105], v[104:105], v[110:111]
	v_pk_add_f32 v[96:97], v[96:97], v[98:99]
	s_nop 0
	v_pk_add_f32 v[96:97], v[104:105], v[96:97]
	s_nop 0
	v_add_f32_e32 v98, v96, v97
	ds_bpermute_b32 v99, v161, v98
	v_or_b32_e32 v96, s25, v210
	v_mov_b32_e32 v97, s31
	s_waitcnt lgkmcnt(0)
	v_add_f32_e32 v98, v98, v99
	ds_bpermute_b32 v99, v202, v98
	s_waitcnt lgkmcnt(0)
	v_add_f32_e32 v98, v98, v99
	v_fmamk_f32 v98, v98, 0x3c800000, v232
	v_cmp_gt_f32_e32 vcc, s96, v98
	v_mul_f32_e32 v99, 0x4b800000, v98
	s_nop 0
	v_cndmask_b32_e32 v98, v98, v99, vcc
	v_rsq_f32_e32 v98, v98
	s_nop 0
	v_mul_f32_e32 v99, 0x45800000, v98
	v_cndmask_b32_e32 v104, v98, v99, vcc
	v_mov_b64_e32 v[98:99], s[8:9]
	v_mad_u64_u32 v[110:111], s[0:1], v96, s97, v[98:99]
	v_mad_i32_i24 v111, s31, v233, v111
	v_lshl_add_u64 v[116:117], v[110:111], 0, s[76:77]
	v_lshl_add_u64 v[122:123], v[116:117], 0, v[150:151]
	global_load_dwordx2 v[224:225], v[122:123], off offset:32
	global_load_dwordx2 v[226:227], v[122:123], off offset:64
	global_load_dwordx2 v[228:229], v[122:123], off offset:96
	global_load_dwordx2 v[122:123], v[122:123], off
	v_lshlrev_b64 v[110:111], 12, v[96:97]
	v_lshl_add_u64 v[110:111], s[6:7], 0, v[110:111]
	v_lshl_add_u64 v[110:111], v[110:111], 0, s[78:79]
	s_waitcnt vmcnt(0)
	v_and_b32_e32 v105, 0xffff0000, v122
	v_lshlrev_b32_e32 v96, 16, v122
	v_pk_mul_f32 v[118:119], v[118:119], v[104:105] op_sel_hi:[1,0]
	v_pk_mul_f32 v[120:121], v[120:121], v[104:105] op_sel_hi:[1,0]
	v_mul_f32_e32 v118, v118, v96
	v_mul_f32_e32 v96, 0xbfb8aa3b, v96
	v_exp_f32_e32 v96, v96
	v_lshlrev_b32_e32 v122, 16, v123
	v_and_b32_e32 v123, 0xffff0000, v123
	v_add_f32_e32 v96, 1.0, v96
	v_rcp_f32_e32 v96, v96
	s_nop 0
	v_mul_f32_e32 v96, v96, v118
	v_mul_f32_e32 v118, v119, v105
	v_mul_f32_e32 v105, 0xbfb8aa3b, v105
	v_exp_f32_e32 v105, v105
	v_mul_f32_e32 v119, 0xbfb8aa3b, v123
	v_exp_f32_e32 v119, v119
	v_add_f32_e32 v105, 1.0, v105
	v_rcp_f32_e32 v105, v105
	v_add_f32_e32 v119, 1.0, v119
	v_rcp_f32_e32 v119, v119
	v_mul_f32_e32 v105, v105, v118
	s_nop 0
	v_cvt_pk_bf16_f32 v118, v96, v105
	v_mul_f32_e32 v105, 0xbfb8aa3b, v122
	v_exp_f32_e32 v105, v105
	v_mul_f32_e32 v96, v120, v122
	v_add_f32_e32 v105, 1.0, v105
	v_rcp_f32_e32 v105, v105
	s_nop 0
	v_mul_f32_e32 v96, v105, v96
	v_mul_f32_e32 v105, v121, v123
	v_mul_f32_e32 v105, v119, v105
	s_nop 0
	v_cvt_pk_bf16_f32 v119, v96, v105
	v_lshl_add_u64 v[120:121], v[110:111], 0, v[150:151]
	global_store_dwordx2 v[120:121], v[118:119], off
	s_waitcnt vmcnt(1)
	v_and_b32_e32 v105, 0xffff0000, v224
	v_lshlrev_b32_e32 v96, 16, v224
	v_pk_mul_f32 v[112:113], v[112:113], v[104:105] op_sel_hi:[1,0]
	v_pk_mul_f32 v[114:115], v[114:115], v[104:105] op_sel_hi:[1,0]
	v_mul_f32_e32 v112, v112, v96
	v_mul_f32_e32 v96, 0xbfb8aa3b, v96
	v_exp_f32_e32 v96, v96
	v_lshlrev_b32_e32 v118, 16, v225
	v_and_b32_e32 v119, 0xffff0000, v225
	v_add_f32_e32 v96, 1.0, v96
	v_rcp_f32_e32 v96, v96
	s_nop 0
	v_mul_f32_e32 v96, v96, v112
	v_mul_f32_e32 v112, v113, v105
	v_mul_f32_e32 v105, 0xbfb8aa3b, v105
	v_exp_f32_e32 v105, v105
	v_mul_f32_e32 v113, 0xbfb8aa3b, v119
	v_exp_f32_e32 v113, v113
	v_add_f32_e32 v105, 1.0, v105
	v_rcp_f32_e32 v105, v105
	v_add_f32_e32 v113, 1.0, v113
	v_rcp_f32_e32 v113, v113
	v_mul_f32_e32 v105, v105, v112
	s_nop 0
	v_cvt_pk_bf16_f32 v112, v96, v105
	v_mul_f32_e32 v105, 0xbfb8aa3b, v118
	v_exp_f32_e32 v105, v105
	v_mul_f32_e32 v96, v114, v118
	v_add_f32_e32 v105, 1.0, v105
	v_rcp_f32_e32 v105, v105
	s_nop 0
	v_mul_f32_e32 v96, v105, v96
	v_mul_f32_e32 v105, v115, v119
	v_mul_f32_e32 v105, v113, v105
	s_nop 0
	v_cvt_pk_bf16_f32 v113, v96, v105
	v_lshl_add_u64 v[114:115], v[110:111], 0, v[152:153]
	global_store_dwordx2 v[114:115], v[112:113], off
	s_waitcnt vmcnt(2)
; __device__ __forceinline__ float shx(float v, int mask, int lane) { return __builtin_bit_cast(float, __builtin_amdgcn_ds_bpermute((lane ^ mask) << 2, __builtin_bit_cast(int, v))); }
; __device__ __forceinline__ float silu_mul(float g, float u) { return g * u * __builtin_amdgcn_rcpf(1.0f + __expf(-g)); }
; __device__ __forceinline__ unsigned pk2(float lo, float hi) { return pg8::cvt_pk_bf16(lo, hi); }
; __device__ __forceinline__ float ex2(float x) { return __builtin_amdgcn_exp2f(x); }
; #define MFMA16(a, b, c) __builtin_amdgcn_mfma_f32_16x16x32_bf16(a, b, c, 0, 0, 0)
; __device__ __forceinline__ void ret_output(Frame& F, const Trunk& T, int layer) {
;     ...
;         for (int qt = 0; qt < 4; ++qt) {
;             const int tau = 64 * half + 16 * qt + i16; const size_t qrow = row0 + tau;
;             const float wqf = ex2(lgf * (float)(tau + 1)), wqb = ex2(lgb * (float)(128 - tau));
;             float s1 = 0.f;
; #pragma unroll
;             for (int nn = 0; nn < 4; ++nn) { const f32x4 xf = MFMA16(rf[nn], qf[qt], z4), xb = MFMA16(rb[nn], qf[qt], z4); o[qt][nn] = o[qt][nn] + xf * wqf + xb * wqb; s1 += (o[qt][nn][0] + o[qt][nn][1]) + (o[qt][nn][2] + o[qt][nn][3]); }
;             s1 += shx(s1, 16, lane); s1 += shx(s1, 32, lane); const float mu = s1 * (1.f / 64.f); float s2 = 0.f;
;     ...
;             for (int nn = 0; nn < 4; ++nn) { const int col = h * 64 + 16 * nn + 4 * quad; const u32x2 gw = *(const u32x2*)(proj + qrow * NIN + C_GR + col);
;                 const float g0 = __uint_as_float(gw.x << 16), g1 = __uint_as_float(gw.x & 0xffff0000u), g2 = __uint_as_float(gw.y << 16), g3 = __uint_as_float(gw.y & 0xffff0000u);
;                 const f32x4 v = o[qt][nn] * rs; u32x2 w; w.x = pk2(pg8::silu_mul(g0, v[0]), pg8::silu_mul(g1, v[1])); w.y = pk2(pg8::silu_mul(g2, v[2]), pg8::silu_mul(g3, v[3]));
;                 *(u32x2*)(mix + qrow * DM + MX_R + col) = w; }
	v_and_b32_e32 v105, 0xffff0000, v226
	v_lshlrev_b32_e32 v96, 16, v226
	v_pk_mul_f32 v[106:107], v[106:107], v[104:105] op_sel_hi:[1,0]
	v_pk_mul_f32 v[108:109], v[108:109], v[104:105] op_sel_hi:[1,0]
	v_mul_f32_e32 v106, v106, v96
	v_mul_f32_e32 v96, 0xbfb8aa3b, v96
	v_exp_f32_e32 v96, v96
	v_lshlrev_b32_e32 v112, 16, v227
	v_and_b32_e32 v113, 0xffff0000, v227
	v_add_f32_e32 v96, 1.0, v96
	v_rcp_f32_e32 v96, v96
	s_nop 0
	v_mul_f32_e32 v96, v96, v106
	v_mul_f32_e32 v106, v107, v105
	v_mul_f32_e32 v105, 0xbfb8aa3b, v105
	v_exp_f32_e32 v105, v105
	v_mul_f32_e32 v107, 0xbfb8aa3b, v113
	v_exp_f32_e32 v107, v107
	v_add_f32_e32 v105, 1.0, v105
	v_rcp_f32_e32 v105, v105
	v_add_f32_e32 v107, 1.0, v107
	v_rcp_f32_e32 v107, v107
	v_mul_f32_e32 v105, v105, v106
	s_nop 0
	v_cvt_pk_bf16_f32 v106, v96, v105
	v_mul_f32_e32 v105, 0xbfb8aa3b, v112
	v_exp_f32_e32 v105, v105
	v_mul_f32_e32 v96, v108, v112
	v_add_f32_e32 v105, 1.0, v105
	v_rcp_f32_e32 v105, v105
	s_nop 0
	v_mul_f32_e32 v96, v105, v96
	v_mul_f32_e32 v105, v109, v113
	v_mul_f32_e32 v105, v107, v105
	s_nop 0
	v_cvt_pk_bf16_f32 v107, v96, v105
	v_lshl_add_u64 v[108:109], v[110:111], 0, v[154:155]
	global_store_dwordx2 v[108:109], v[106:107], off
	s_waitcnt vmcnt(3)
	v_and_b32_e32 v105, 0xffff0000, v228
	v_lshlrev_b32_e32 v96, 16, v228
	v_pk_mul_f32 v[100:101], v[100:101], v[104:105] op_sel_hi:[1,0]
	v_lshlrev_b32_e32 v106, 16, v229
	v_mul_f32_e32 v100, v100, v96
	v_mul_f32_e32 v96, 0xbfb8aa3b, v96
	v_exp_f32_e32 v96, v96
	v_and_b32_e32 v107, 0xffff0000, v229
	v_pk_mul_f32 v[102:103], v[102:103], v[104:105] op_sel_hi:[1,0]
	v_add_f32_e32 v96, 1.0, v96
	v_rcp_f32_e32 v96, v96
	s_nop 0
	v_mul_f32_e32 v96, v96, v100
	v_mul_f32_e32 v100, v101, v105
	v_mul_f32_e32 v101, 0xbfb8aa3b, v105
	v_exp_f32_e32 v101, v101
	s_nop 0
	v_add_f32_e32 v101, 1.0, v101
	v_rcp_f32_e32 v101, v101
	s_nop 0
	v_mul_f32_e32 v100, v101, v100
	v_mul_f32_e32 v101, 0xbfb8aa3b, v106
	s_nop 0
	v_cvt_pk_bf16_f32 v100, v96, v100
	v_mul_f32_e32 v96, v102, v106
	v_exp_f32_e32 v101, v101
	v_mul_f32_e32 v102, 0xbfb8aa3b, v107
	v_exp_f32_e32 v102, v102
	v_add_f32_e32 v101, 1.0, v101
	v_rcp_f32_e32 v101, v101
	v_add_f32_e32 v102, 1.0, v102
	v_rcp_f32_e32 v102, v102
	v_mul_f32_e32 v96, v101, v96
	v_mul_f32_e32 v101, v103, v107
	v_mul_f32_e32 v101, v102, v101
	s_nop 0
	v_cvt_pk_bf16_f32 v101, v96, v101
	v_add_u32_e32 v96, 33, v147
	v_cvt_f32_u32_e32 v96, v96
	v_lshl_add_u64 v[102:103], v[110:111], 0, v[166:167]
	global_store_dwordx2 v[102:103], v[100:101], off
	v_sub_u32_e32 v100, 0x80, v209
	v_cvt_f32_ubyte0_e32 v100, v100
	v_mul_f32_e32 v96, v207, v96
	v_mul_f32_e32 v100, v208, v100
	v_exp_f32_e32 v96, v96
	v_exp_f32_e32 v108, v100
	v_mfma_f32_16x16x32_bf16 v[100:103], v[44:47], v[76:79], 0
	v_mfma_f32_16x16x32_bf16 v[104:107], v[48:51], v[76:79], 0
	v_mfma_f32_16x16x32_bf16 v[44:47], v[44:47], v[24:27], 0
	s_nop 5
	v_fma_f32 v86, v96, v102, v86
	v_fma_f32 v87, v96, v103, v87
	v_pk_fma_f32 v[84:85], v[96:97], v[100:101], v[84:85] op_sel_hi:[0,1,1]
	v_pk_fma_f32 v[106:107], v[108:109], v[106:107], v[86:87] op_sel_hi:[0,1,1]
	v_pk_fma_f32 v[104:105], v[108:109], v[104:105], v[84:85] op_sel_hi:[0,1,1]
	v_pk_mov_b32 v[84:85], v[104:105], v[106:107] op_sel:[1,0]
	v_mov_b32_e32 v86, v104
	v_mov_b32_e32 v87, v107
	v_pk_add_f32 v[84:85], v[84:85], v[86:87]
	v_mfma_f32_16x16x32_bf16 v[100:103], v[56:59], v[76:79], 0
	v_add_f32_e32 v84, v84, v85
	v_add_f32_e32 v110, 0, v84
	v_mfma_f32_16x16x32_bf16 v[84:87], v[52:55], v[76:79], 0
	v_mfma_f32_16x16x32_bf16 v[48:51], v[48:51], v[24:27], 0
	s_nop 6
	v_fma_f32 v82, v96, v86, v82
	v_fma_f32 v83, v96, v87, v83
	v_pk_fma_f32 v[80:81], v[96:97], v[84:85], v[80:81] op_sel_hi:[0,1,1]
	v_pk_fma_f32 v[102:103], v[108:109], v[102:103], v[82:83] op_sel_hi:[0,1,1]
	v_pk_fma_f32 v[100:101], v[108:109], v[100:101], v[80:81] op_sel_hi:[0,1,1]
	v_pk_mov_b32 v[80:81], v[100:101], v[102:103] op_sel:[1,0]
	v_mov_b32_e32 v82, v100
	v_mov_b32_e32 v83, v103
	v_pk_add_f32 v[80:81], v[80:81], v[82:83]
	v_mfma_f32_16x16x32_bf16 v[84:87], v[64:67], v[76:79], 0
	v_add_f32_e64 v112, v80, v81
	v_add_f32_e64 v113, v81, v80
	v_mfma_f32_16x16x32_bf16 v[80:83], v[60:63], v[76:79], 0
	s_nop 7
	v_pk_fma_f32 v[82:83], v[96:97], v[82:83], v[94:95] op_sel_hi:[0,1,1]
	v_pk_fma_f32 v[80:81], v[96:97], v[80:81], v[92:93] op_sel_hi:[0,1,1]
	v_pk_fma_f32 v[82:83], v[108:109], v[86:87], v[82:83] op_sel_hi:[0,1,1]
	v_pk_fma_f32 v[80:81], v[108:109], v[84:85], v[80:81] op_sel_hi:[0,1,1]
	v_mfma_f32_16x16x32_bf16 v[84:87], v[68:71], v[76:79], 0
	v_add_f32_e32 v92, v80, v81
	v_add_f32_e32 v94, v82, v83
	v_mfma_f32_16x16x32_bf16 v[76:79], v[72:75], v[76:79], 0
	s_nop 4
	v_fma_f32 v86, v96, v86, v90
	v_fma_f32 v87, v96, v87, v91
	v_pk_fma_f32 v[84:85], v[96:97], v[84:85], v[88:89] op_sel_hi:[0,1,1]
	v_pk_fma_f32 v[78:79], v[108:109], v[78:79], v[86:87] op_sel_hi:[0,1,1]
	v_pk_fma_f32 v[76:77], v[108:109], v[76:77], v[84:85] op_sel_hi:[0,1,1]
	v_mov_b32_e32 v111, v76
	v_mov_b32_e32 v113, v77
	v_mov_b32_e32 v93, v78
	v_mov_b32_e32 v95, v79
	v_pk_add_f32 v[84:85], v[110:111], v[112:113]
	v_pk_add_f32 v[86:87], v[92:93], v[94:95]
	v_or_b32_e32 v96, s25, v209
	v_pk_add_f32 v[84:85], v[84:85], v[86:87]
	s_nop 0
	v_add_f32_e32 v84, v84, v85
	ds_bpermute_b32 v85, v161, v84
	s_waitcnt lgkmcnt(0)
	v_add_f32_e32 v84, v84, v85
	ds_bpermute_b32 v85, v202, v84
	s_waitcnt lgkmcnt(0)
; __device__ __forceinline__ float shx(float v, int mask, int lane) { return __builtin_bit_cast(float, __builtin_amdgcn_ds_bpermute((lane ^ mask) << 2, __builtin_bit_cast(int, v))); }
; __device__ __forceinline__ float silu_mul(float g, float u) { return g * u * __builtin_amdgcn_rcpf(1.0f + __expf(-g)); }
; __device__ __forceinline__ unsigned pk2(float lo, float hi) { return pg8::cvt_pk_bf16(lo, hi); }
; __device__ __forceinline__ void ret_output(Frame& F, const Trunk& T, int layer) {
;     ...
;             s1 += shx(s1, 16, lane); s1 += shx(s1, 32, lane); const float mu = s1 * (1.f / 64.f); float s2 = 0.f;
; #pragma unroll
;             for (int nn = 0; nn < 4; ++nn) { o[qt][nn] = o[qt][nn] - mu; s2 += (o[qt][nn][0] * o[qt][nn][0] + o[qt][nn][1] * o[qt][nn][1]) + (o[qt][nn][2] * o[qt][nn][2] + o[qt][nn][3] * o[qt][nn][3]); }
;             s2 += shx(s2, 16, lane); s2 += shx(s2, 32, lane); const float rs = rsqrtf(s2 * (1.f / 64.f) + 1e-5f);
; #pragma unroll
;             for (int nn = 0; nn < 4; ++nn) { const int col = h * 64 + 16 * nn + 4 * quad; const u32x2 gw = *(const u32x2*)(proj + qrow * NIN + C_GR + col);
;                 const float g0 = __uint_as_float(gw.x << 16), g1 = __uint_as_float(gw.x & 0xffff0000u), g2 = __uint_as_float(gw.y << 16), g3 = __uint_as_float(gw.y & 0xffff0000u);
;                 const f32x4 v = o[qt][nn] * rs; u32x2 w; w.x = pk2(pg8::silu_mul(g0, v[0]), pg8::silu_mul(g1, v[1])); w.y = pk2(pg8::silu_mul(g2, v[2]), pg8::silu_mul(g3, v[3]));
;                 *(u32x2*)(mix + qrow * DM + MX_R + col) = w; }
	v_add_f32_e32 v92, v84, v85
	v_fmamk_f32 v105, v92, 0xbc800000, v105
	v_fmac_f32_e32 v104, 0xbc800000, v92
	v_fmamk_f32 v107, v92, 0xbc800000, v107
	v_fmac_f32_e32 v106, 0xbc800000, v92
	v_pk_mul_f32 v[84:85], v[106:107], v[106:107]
	v_pk_mul_f32 v[86:87], v[104:105], v[104:105]
	v_fmamk_f32 v101, v92, 0xbc800000, v101
	v_pk_mov_b32 v[88:89], v[86:87], v[84:85] op_sel:[1,0]
	v_mov_b32_e32 v87, v85
	v_fmac_f32_e32 v100, 0xbc800000, v92
	v_fmamk_f32 v103, v92, 0xbc800000, v103
	v_fmac_f32_e32 v102, 0xbc800000, v92
	v_pk_add_f32 v[84:85], v[88:89], v[86:87]
	v_pk_mul_f32 v[86:87], v[102:103], v[102:103]
	v_pk_mul_f32 v[88:89], v[100:101], v[100:101]
	v_pk_add_f32 v[84:85], v[84:85], v[84:85] op_sel_hi:[0,1]
	v_pk_mov_b32 v[90:91], v[88:89], v[86:87] op_sel:[1,0]
	v_mov_b32_e32 v89, v87
	v_fmac_f32_e32 v80, 0xbc800000, v92
	v_pk_add_f32 v[86:87], v[90:91], v[88:89]
	v_fmamk_f32 v81, v92, 0xbc800000, v81
	v_fmac_f32_e32 v82, 0xbc800000, v92
	v_mul_f32_e32 v84, v80, v80
	v_pk_add_f32 v[86:87], v[86:87], v[86:87] op_sel_hi:[0,1]
	v_fmamk_f32 v83, v92, 0xbc800000, v83
	v_pk_fma_f32 v[88:89], v[80:81], v[80:81], v[84:85] op_sel_hi:[1,1,0]
	v_mul_f32_e32 v84, v82, v82
	v_fmamk_f32 v79, v92, 0xbc800000, v79
	v_fmac_f32_e32 v78, 0xbc800000, v92
	v_pk_fma_f32 v[90:91], v[82:83], v[82:83], v[84:85] op_sel_hi:[1,1,0]
	v_fmamk_f32 v77, v92, 0xbc800000, v77
	v_fmac_f32_e32 v76, 0xbc800000, v92
	v_mul_f32_e32 v84, v78, v78
	v_mul_f32_e32 v86, v79, v79
	v_mul_f32_e32 v88, v76, v76
	v_mul_f32_e32 v90, v77, v77
	v_pk_add_f32 v[84:85], v[84:85], v[86:87]
	v_mad_u64_u32 v[86:87], s[0:1], v96, s97, v[98:99]
	v_pk_add_f32 v[88:89], v[88:89], v[90:91]
	v_mad_i32_i24 v87, s31, v233, v87
	v_pk_add_f32 v[84:85], v[88:89], v[84:85]
	v_lshl_add_u64 v[88:89], v[86:87], 0, s[76:77]
	v_lshl_add_u64 v[90:91], v[88:89], 0, v[150:151]
	global_load_dwordx2 v[224:225], v[90:91], off offset:32
	global_load_dwordx2 v[226:227], v[90:91], off offset:64
	global_load_dwordx2 v[228:229], v[90:91], off offset:96
	global_load_dwordx2 v[90:91], v[90:91], off
	v_add_f32_e32 v84, v84, v85
	ds_bpermute_b32 v85, v161, v84
	v_lshlrev_b64 v[86:87], 12, v[96:97]
	v_lshl_add_u64 v[86:87], s[6:7], 0, v[86:87]
	v_lshl_add_u64 v[86:87], v[86:87], 0, s[78:79]
	s_waitcnt lgkmcnt(0)
	v_add_f32_e32 v84, v84, v85
	ds_bpermute_b32 v85, v202, v84
	s_waitcnt lgkmcnt(0)
	v_add_f32_e32 v84, v84, v85
	v_fmamk_f32 v84, v84, 0x3c800000, v232
	v_cmp_gt_f32_e32 vcc, s96, v84
	v_mul_f32_e32 v85, 0x4b800000, v84
	s_waitcnt vmcnt(0)
	v_and_b32_e32 v94, 0xffff0000, v90
	v_cndmask_b32_e32 v84, v84, v85, vcc
	v_rsq_f32_e32 v84, v84
	v_lshlrev_b32_e32 v95, 16, v91
	v_and_b32_e32 v96, 0xffff0000, v91
	v_mul_f32_e32 v85, 0x45800000, v84
	v_cndmask_b32_e32 v84, v84, v85, vcc
	v_lshlrev_b32_e32 v85, 16, v90
	v_pk_mul_f32 v[92:93], v[104:105], v[84:85] op_sel_hi:[1,0]
	v_pk_mul_f32 v[90:91], v[106:107], v[84:85] op_sel_hi:[1,0]
	v_mul_f32_e32 v92, v92, v85
	v_mul_f32_e32 v85, 0xbfb8aa3b, v85
	v_exp_f32_e32 v85, v85
	s_nop 0
	v_add_f32_e32 v85, 1.0, v85
	v_rcp_f32_e32 v85, v85
	s_nop 0
	v_mul_f32_e32 v85, v85, v92
	v_mul_f32_e32 v92, v93, v94
	v_mul_f32_e32 v93, 0xbfb8aa3b, v94
	v_exp_f32_e32 v93, v93
	s_nop 0
	v_add_f32_e32 v93, 1.0, v93
	v_rcp_f32_e32 v93, v93
	s_nop 0
	v_mul_f32_e32 v92, v93, v92
	s_nop 0
	v_cvt_pk_bf16_f32 v92, v85, v92
	v_mul_f32_e32 v85, v90, v95
	v_mul_f32_e32 v90, 0xbfb8aa3b, v95
	v_exp_f32_e32 v90, v90
	s_nop 0
	v_add_f32_e32 v90, 1.0, v90
	v_rcp_f32_e32 v90, v90
	s_nop 0
	v_mul_f32_e32 v85, v90, v85
	v_mul_f32_e32 v90, v91, v96
	v_mul_f32_e32 v91, 0xbfb8aa3b, v96
	v_exp_f32_e32 v91, v91
	s_nop 0
	v_add_f32_e32 v91, 1.0, v91
	v_rcp_f32_e32 v91, v91
	s_nop 0
	v_mul_f32_e32 v90, v91, v90
	s_nop 0
	v_cvt_pk_bf16_f32 v93, v85, v90
	v_lshl_add_u64 v[90:91], v[86:87], 0, v[150:151]
	global_store_dwordx2 v[90:91], v[92:93], off
	s_waitcnt vmcnt(1)
	v_lshlrev_b32_e32 v85, 16, v224
	v_pk_mul_f32 v[92:93], v[100:101], v[84:85] op_sel_hi:[1,0]
	v_and_b32_e32 v94, 0xffff0000, v224
	v_lshlrev_b32_e32 v95, 16, v225
	v_and_b32_e32 v96, 0xffff0000, v225
	v_pk_mul_f32 v[90:91], v[102:103], v[84:85] op_sel_hi:[1,0]
	v_mul_f32_e32 v92, v92, v85
	v_mul_f32_e32 v85, 0xbfb8aa3b, v85
	v_exp_f32_e32 v85, v85
	s_nop 0
	v_add_f32_e32 v85, 1.0, v85
	v_rcp_f32_e32 v85, v85
	s_nop 0
	v_mul_f32_e32 v85, v85, v92
	v_mul_f32_e32 v92, v93, v94
	v_mul_f32_e32 v93, 0xbfb8aa3b, v94
	v_exp_f32_e32 v93, v93
	s_nop 0
	v_add_f32_e32 v93, 1.0, v93
	v_rcp_f32_e32 v93, v93
	s_nop 0
	v_mul_f32_e32 v92, v93, v92
	s_nop 0
	v_cvt_pk_bf16_f32 v92, v85, v92
	v_mul_f32_e32 v85, v90, v95
	v_mul_f32_e32 v90, 0xbfb8aa3b, v95
	v_exp_f32_e32 v90, v90
	s_nop 0
	v_add_f32_e32 v90, 1.0, v90
	v_rcp_f32_e32 v90, v90
	s_nop 0
	v_mul_f32_e32 v85, v90, v85
	v_mul_f32_e32 v90, v91, v96
	v_mul_f32_e32 v91, 0xbfb8aa3b, v96
	v_exp_f32_e32 v91, v91
	v_or_b32_e32 v96, s25, v149
	v_add_f32_e32 v91, 1.0, v91
	v_rcp_f32_e32 v91, v91
	s_nop 0
	v_mul_f32_e32 v90, v91, v90
	s_nop 0
	v_cvt_pk_bf16_f32 v93, v85, v90
	v_lshl_add_u64 v[90:91], v[86:87], 0, v[152:153]
	global_store_dwordx2 v[90:91], v[92:93], off
	s_waitcnt vmcnt(2)
; __device__ __forceinline__ float shx(float v, int mask, int lane) { return __builtin_bit_cast(float, __builtin_amdgcn_ds_bpermute((lane ^ mask) << 2, __builtin_bit_cast(int, v))); }
; __device__ __forceinline__ float silu_mul(float g, float u) { return g * u * __builtin_amdgcn_rcpf(1.0f + __expf(-g)); }
; __device__ __forceinline__ unsigned pk2(float lo, float hi) { return pg8::cvt_pk_bf16(lo, hi); }
; __device__ __forceinline__ float ex2(float x) { return __builtin_amdgcn_exp2f(x); }
; #define MFMA16(a, b, c) __builtin_amdgcn_mfma_f32_16x16x32_bf16(a, b, c, 0, 0, 0)
; __device__ __forceinline__ void ret_output(Frame& F, const Trunk& T, int layer) {
;     ...
;         for (int qt = 0; qt < 4; ++qt) {
;             const int tau = 64 * half + 16 * qt + i16; const size_t qrow = row0 + tau;
;             const float wqf = ex2(lgf * (float)(tau + 1)), wqb = ex2(lgb * (float)(128 - tau));
;             float s1 = 0.f;
; #pragma unroll
;             for (int nn = 0; nn < 4; ++nn) { const f32x4 xf = MFMA16(rf[nn], qf[qt], z4), xb = MFMA16(rb[nn], qf[qt], z4); o[qt][nn] = o[qt][nn] + xf * wqf + xb * wqb; s1 += (o[qt][nn][0] + o[qt][nn][1]) + (o[qt][nn][2] + o[qt][nn][3]); }
;             s1 += shx(s1, 16, lane); s1 += shx(s1, 32, lane); const float mu = s1 * (1.f / 64.f); float s2 = 0.f;
;     ...
;             for (int nn = 0; nn < 4; ++nn) { const int col = h * 64 + 16 * nn + 4 * quad; const u32x2 gw = *(const u32x2*)(proj + qrow * NIN + C_GR + col);
;                 const float g0 = __uint_as_float(gw.x << 16), g1 = __uint_as_float(gw.x & 0xffff0000u), g2 = __uint_as_float(gw.y << 16), g3 = __uint_as_float(gw.y & 0xffff0000u);
;                 const f32x4 v = o[qt][nn] * rs; u32x2 w; w.x = pk2(pg8::silu_mul(g0, v[0]), pg8::silu_mul(g1, v[1])); w.y = pk2(pg8::silu_mul(g2, v[2]), pg8::silu_mul(g3, v[3]));
;                 *(u32x2*)(mix + qrow * DM + MX_R + col) = w; }
	v_lshlrev_b32_e32 v85, 16, v226
	v_pk_mul_f32 v[80:81], v[80:81], v[84:85] op_sel_hi:[1,0]
	v_pk_mul_f32 v[82:83], v[82:83], v[84:85] op_sel_hi:[1,0]
	v_mul_f32_e32 v80, v80, v85
	v_mul_f32_e32 v85, 0xbfb8aa3b, v85
	v_exp_f32_e32 v85, v85
	v_and_b32_e32 v90, 0xffff0000, v226
	v_mul_f32_e32 v81, v81, v90
	v_lshlrev_b32_e32 v92, 16, v227
	v_add_f32_e32 v85, 1.0, v85
	v_rcp_f32_e32 v85, v85
	v_and_b32_e32 v91, 0xffff0000, v227
	v_mul_f32_e32 v80, v85, v80
	v_mul_f32_e32 v85, 0xbfb8aa3b, v90
	v_exp_f32_e32 v85, v85
	s_nop 0
	v_add_f32_e32 v85, 1.0, v85
	v_rcp_f32_e32 v85, v85
	s_nop 0
	v_mul_f32_e32 v81, v85, v81
	s_nop 0
	v_cvt_pk_bf16_f32 v80, v80, v81
	v_mul_f32_e32 v81, v82, v92
	v_mul_f32_e32 v82, 0xbfb8aa3b, v92
	v_exp_f32_e32 v82, v82
	v_pk_mul_f32 v[76:77], v[76:77], v[84:85] op_sel_hi:[1,0]
	v_pk_mul_f32 v[78:79], v[78:79], v[84:85] op_sel_hi:[1,0]
	v_add_f32_e32 v82, 1.0, v82
	v_rcp_f32_e32 v82, v82
	s_nop 0
	v_mul_f32_e32 v81, v82, v81
	v_mul_f32_e32 v82, v83, v91
	v_mul_f32_e32 v83, 0xbfb8aa3b, v91
	v_exp_f32_e32 v83, v83
	s_nop 0
	v_add_f32_e32 v83, 1.0, v83
	v_rcp_f32_e32 v83, v83
	s_nop 0
	v_mul_f32_e32 v82, v83, v82
	s_nop 0
	v_cvt_pk_bf16_f32 v81, v81, v82
	v_lshl_add_u64 v[82:83], v[86:87], 0, v[154:155]
	global_store_dwordx2 v[82:83], v[80:81], off
	s_waitcnt vmcnt(3)
	v_lshlrev_b32_e32 v82, 16, v228
	v_and_b32_e32 v80, 0xffff0000, v228
	v_mul_f32_e32 v76, v76, v82
	v_mul_f32_e32 v82, 0xbfb8aa3b, v82
	v_mul_f32_e32 v77, v77, v80
	v_mul_f32_e32 v80, 0xbfb8aa3b, v80
	v_exp_f32_e32 v82, v82
	v_exp_f32_e32 v80, v80
	v_lshlrev_b32_e32 v83, 16, v229
	v_and_b32_e32 v81, 0xffff0000, v229
	v_add_f32_e32 v82, 1.0, v82
	v_add_f32_e32 v80, 1.0, v80
	v_rcp_f32_e32 v82, v82
	v_rcp_f32_e32 v80, v80
	v_mul_f32_e32 v76, v82, v76
	v_mul_f32_e32 v77, v80, v77
	s_nop 0
	v_cvt_pk_bf16_f32 v76, v76, v77
	v_mul_f32_e32 v77, v78, v83
	v_mul_f32_e32 v78, 0xbfb8aa3b, v83
	v_exp_f32_e32 v78, v78
	s_nop 0
	v_add_f32_e32 v78, 1.0, v78
	v_rcp_f32_e32 v78, v78
	s_nop 0
	v_mul_f32_e32 v77, v78, v77
	v_mul_f32_e32 v78, v79, v81
	v_mul_f32_e32 v79, 0xbfb8aa3b, v81
	v_exp_f32_e32 v79, v79
	s_nop 0
	v_add_f32_e32 v79, 1.0, v79
	v_rcp_f32_e32 v79, v79
	s_nop 0
	v_mul_f32_e32 v78, v79, v78
	s_nop 0
	v_cvt_pk_bf16_f32 v77, v77, v78
	v_lshl_add_u64 v[78:79], v[86:87], 0, v[166:167]
	global_store_dwordx2 v[78:79], v[76:77], off
	v_add_u32_e32 v76, 49, v147
	v_cvt_f32_u32_e32 v76, v76
	v_sub_u32_e32 v77, 0x80, v149
	v_cvt_f32_ubyte0_e32 v77, v77
	v_mul_f32_e32 v77, v208, v77
	v_mul_f32_e32 v76, v207, v76
	v_exp_f32_e32 v76, v76
	v_exp_f32_e32 v78, v77
	v_pk_fma_f32 v[42:43], v[76:77], v[46:47], v[42:43] op_sel_hi:[0,1,1]
	v_pk_fma_f32 v[40:41], v[76:77], v[44:45], v[40:41] op_sel_hi:[0,1,1]
	v_pk_fma_f32 v[44:45], v[78:79], v[50:51], v[42:43] op_sel_hi:[0,1,1]
	v_pk_fma_f32 v[42:43], v[78:79], v[48:49], v[40:41] op_sel_hi:[0,1,1]
	v_pk_mov_b32 v[40:41], v[42:43], v[44:45] op_sel:[1,0]
	v_mov_b32_e32 v46, v42
	v_mov_b32_e32 v47, v45
	v_pk_add_f32 v[40:41], v[40:41], v[46:47]
	v_mfma_f32_16x16x32_bf16 v[46:49], v[52:55], v[24:27], 0
	v_add_f32_e32 v40, v40, v41
	v_add_f32_e32 v40, 0, v40
	v_mfma_f32_16x16x32_bf16 v[50:53], v[56:59], v[24:27], 0
	s_nop 4
	v_fma_f32 v38, v76, v48, v38
	v_fma_f32 v39, v76, v49, v39
	v_pk_fma_f32 v[36:37], v[76:77], v[46:47], v[36:37] op_sel_hi:[0,1,1]
	v_pk_fma_f32 v[38:39], v[78:79], v[52:53], v[38:39] op_sel_hi:[0,1,1]
	v_pk_fma_f32 v[36:37], v[78:79], v[50:51], v[36:37] op_sel_hi:[0,1,1]
	v_pk_mov_b32 v[46:47], v[36:37], v[38:39] op_sel:[1,0]
	v_mov_b32_e32 v48, v36
	v_mov_b32_e32 v49, v39
	v_pk_add_f32 v[46:47], v[46:47], v[48:49]
	v_mfma_f32_16x16x32_bf16 v[50:53], v[64:67], v[24:27], 0
	v_add_f32_e64 v54, v46, v47
	v_add_f32_e64 v55, v47, v46
	v_mfma_f32_16x16x32_bf16 v[46:49], v[60:63], v[24:27], 0
	s_nop 7
	v_pk_fma_f32 v[34:35], v[76:77], v[48:49], v[34:35] op_sel_hi:[0,1,1]
	v_pk_fma_f32 v[32:33], v[76:77], v[46:47], v[32:33] op_sel_hi:[0,1,1]
	v_mfma_f32_16x16x32_bf16 v[46:49], v[68:71], v[24:27], 0
	v_fma_f32 v34, v78, v52, v34
	v_fma_f32 v35, v78, v53, v35
	v_pk_fma_f32 v[32:33], v[78:79], v[50:51], v[32:33] op_sel_hi:[0,1,1]
	v_add_f32_e32 v50, v32, v33
	v_mfma_f32_16x16x32_bf16 v[24:27], v[72:75], v[24:27], 0
	v_add_f32_e32 v52, v34, v35
	s_nop 1
	v_pk_fma_f32 v[30:31], v[76:77], v[48:49], v[30:31] op_sel_hi:[0,1,1]
	v_pk_fma_f32 v[28:29], v[76:77], v[46:47], v[28:29] op_sel_hi:[0,1,1]
	s_nop 2
	v_pk_fma_f32 v[26:27], v[78:79], v[26:27], v[30:31] op_sel_hi:[0,1,1]
	v_pk_fma_f32 v[24:25], v[78:79], v[24:25], v[28:29] op_sel_hi:[0,1,1]
	v_mov_b32_e32 v41, v24
	v_mov_b32_e32 v55, v25
	v_mov_b32_e32 v51, v26
	v_mov_b32_e32 v53, v27
	v_pk_add_f32 v[28:29], v[40:41], v[54:55]
	v_pk_add_f32 v[30:31], v[50:51], v[52:53]
	s_nop 0
	v_pk_add_f32 v[28:29], v[28:29], v[30:31]
	s_nop 0
	v_add_f32_e32 v28, v28, v29
	ds_bpermute_b32 v29, v161, v28
	s_waitcnt lgkmcnt(0)
	v_add_f32_e32 v28, v28, v29
	ds_bpermute_b32 v29, v202, v28
	s_waitcnt lgkmcnt(0)
; __device__ __forceinline__ float shx(float v, int mask, int lane) { return __builtin_bit_cast(float, __builtin_amdgcn_ds_bpermute((lane ^ mask) << 2, __builtin_bit_cast(int, v))); }
; __device__ __forceinline__ float silu_mul(float g, float u) { return g * u * __builtin_amdgcn_rcpf(1.0f + __expf(-g)); }
; __device__ __forceinline__ unsigned pk2(float lo, float hi) { return pg8::cvt_pk_bf16(lo, hi); }
; __device__ __forceinline__ void ret_output(Frame& F, const Trunk& T, int layer) {
;     ...
;             s1 += shx(s1, 16, lane); s1 += shx(s1, 32, lane); const float mu = s1 * (1.f / 64.f); float s2 = 0.f;
; #pragma unroll
;             for (int nn = 0; nn < 4; ++nn) { o[qt][nn] = o[qt][nn] - mu; s2 += (o[qt][nn][0] * o[qt][nn][0] + o[qt][nn][1] * o[qt][nn][1]) + (o[qt][nn][2] * o[qt][nn][2] + o[qt][nn][3] * o[qt][nn][3]); }
;             s2 += shx(s2, 16, lane); s2 += shx(s2, 32, lane); const float rs = rsqrtf(s2 * (1.f / 64.f) + 1e-5f);
; #pragma unroll
;             for (int nn = 0; nn < 4; ++nn) { const int col = h * 64 + 16 * nn + 4 * quad; const u32x2 gw = *(const u32x2*)(proj + qrow * NIN + C_GR + col);
;                 const float g0 = __uint_as_float(gw.x << 16), g1 = __uint_as_float(gw.x & 0xffff0000u), g2 = __uint_as_float(gw.y << 16), g3 = __uint_as_float(gw.y & 0xffff0000u);
;                 const f32x4 v = o[qt][nn] * rs; u32x2 w; w.x = pk2(pg8::silu_mul(g0, v[0]), pg8::silu_mul(g1, v[1])); w.y = pk2(pg8::silu_mul(g2, v[2]), pg8::silu_mul(g3, v[3]));
;                 *(u32x2*)(mix + qrow * DM + MX_R + col) = w; }
	v_add_f32_e32 v48, v28, v29
	v_fmamk_f32 v43, v48, 0xbc800000, v43
	v_fmac_f32_e32 v42, 0xbc800000, v48
	v_fmamk_f32 v45, v48, 0xbc800000, v45
	v_fmac_f32_e32 v44, 0xbc800000, v48
	v_pk_mul_f32 v[28:29], v[44:45], v[44:45]
	v_pk_mul_f32 v[30:31], v[42:43], v[42:43]
	v_fmamk_f32 v37, v48, 0xbc800000, v37
	v_pk_mov_b32 v[40:41], v[30:31], v[28:29] op_sel:[1,0]
	v_mov_b32_e32 v31, v29
	v_fmac_f32_e32 v36, 0xbc800000, v48
	v_fmamk_f32 v39, v48, 0xbc800000, v39
	v_fmac_f32_e32 v38, 0xbc800000, v48
	v_pk_add_f32 v[28:29], v[40:41], v[30:31]
	v_pk_mul_f32 v[30:31], v[38:39], v[38:39]
	v_pk_mul_f32 v[40:41], v[36:37], v[36:37]
	v_pk_add_f32 v[28:29], v[28:29], v[28:29] op_sel_hi:[0,1]
	v_pk_mov_b32 v[46:47], v[40:41], v[30:31] op_sel:[1,0]
	v_mov_b32_e32 v41, v31
	v_fmac_f32_e32 v32, 0xbc800000, v48
	v_pk_add_f32 v[30:31], v[46:47], v[40:41]
	v_fmamk_f32 v33, v48, 0xbc800000, v33
	v_fmac_f32_e32 v34, 0xbc800000, v48
	v_mul_f32_e32 v28, v32, v32
	v_pk_add_f32 v[30:31], v[30:31], v[30:31] op_sel_hi:[0,1]
	v_fmamk_f32 v35, v48, 0xbc800000, v35
	v_pk_fma_f32 v[40:41], v[32:33], v[32:33], v[28:29] op_sel_hi:[1,1,0]
	v_mul_f32_e32 v28, v34, v34
	v_fmamk_f32 v27, v48, 0xbc800000, v27
	v_fmac_f32_e32 v26, 0xbc800000, v48
	v_pk_fma_f32 v[46:47], v[34:35], v[34:35], v[28:29] op_sel_hi:[1,1,0]
	v_fmamk_f32 v25, v48, 0xbc800000, v25
	v_fmac_f32_e32 v24, 0xbc800000, v48
	v_mul_f32_e32 v28, v26, v26
	v_mul_f32_e32 v30, v27, v27
	v_mul_f32_e32 v40, v24, v24
	v_mul_f32_e32 v46, v25, v25
	v_pk_add_f32 v[28:29], v[28:29], v[30:31]
	v_mad_u64_u32 v[30:31], s[0:1], v96, s97, v[98:99]
	v_pk_add_f32 v[40:41], v[40:41], v[46:47]
	v_mad_i32_i24 v31, s31, v233, v31
	v_pk_add_f32 v[28:29], v[40:41], v[28:29]
	v_lshl_add_u64 v[40:41], v[30:31], 0, s[76:77]
	v_lshl_add_u64 v[46:47], v[40:41], 0, v[150:151]
	global_load_dwordx2 v[224:225], v[46:47], off offset:32
	global_load_dwordx2 v[226:227], v[46:47], off offset:64
	global_load_dwordx2 v[228:229], v[46:47], off offset:96
	global_load_dwordx2 v[46:47], v[46:47], off
	v_add_f32_e32 v28, v28, v29
	ds_bpermute_b32 v29, v161, v28
	v_lshlrev_b64 v[30:31], 12, v[96:97]
	v_lshl_add_u64 v[30:31], s[6:7], 0, v[30:31]
	v_lshl_add_u64 v[30:31], v[30:31], 0, s[78:79]
	s_mov_b64 s[0:1], 0
	s_waitcnt lgkmcnt(0)
	v_add_f32_e32 v28, v28, v29
	ds_bpermute_b32 v29, v202, v28
	s_waitcnt lgkmcnt(0)
	v_add_f32_e32 v28, v28, v29
	v_fmamk_f32 v28, v28, 0x3c800000, v232
	v_cmp_gt_f32_e32 vcc, s96, v28
	v_mul_f32_e32 v29, 0x4b800000, v28
	s_waitcnt vmcnt(0)
	v_lshlrev_b32_e32 v48, 16, v47
	v_cndmask_b32_e32 v28, v28, v29, vcc
	v_rsq_f32_e32 v28, v28
	v_and_b32_e32 v47, 0xffff0000, v47
	v_mul_f32_e32 v29, 0x45800000, v28
	v_cndmask_b32_e32 v28, v28, v29, vcc
	v_lshlrev_b32_e32 v29, 16, v46
	v_pk_mul_f32 v[42:43], v[42:43], v[28:29] op_sel_hi:[1,0]
	v_pk_mul_f32 v[44:45], v[44:45], v[28:29] op_sel_hi:[1,0]
	v_mul_f32_e32 v42, v42, v29
	v_mul_f32_e32 v29, 0xbfb8aa3b, v29
	v_exp_f32_e32 v29, v29
	v_and_b32_e32 v46, 0xffff0000, v46
	s_and_b64 vcc, exec, s[54:55]
	v_add_f32_e32 v29, 1.0, v29
	v_rcp_f32_e32 v29, v29
	s_nop 0
	v_mul_f32_e32 v29, v29, v42
	v_mul_f32_e32 v42, v43, v46
	v_mul_f32_e32 v43, 0xbfb8aa3b, v46
	v_exp_f32_e32 v43, v43
	s_nop 0
	v_add_f32_e32 v43, 1.0, v43
	v_rcp_f32_e32 v43, v43
	s_nop 0
	v_mul_f32_e32 v42, v43, v42
	v_mul_f32_e32 v43, 0xbfb8aa3b, v48
	s_nop 0
	v_cvt_pk_bf16_f32 v42, v29, v42
	v_mul_f32_e32 v29, v44, v48
	v_exp_f32_e32 v43, v43
	v_mul_f32_e32 v44, 0xbfb8aa3b, v47
	v_exp_f32_e32 v44, v44
	v_add_f32_e32 v43, 1.0, v43
	v_rcp_f32_e32 v43, v43
	v_add_f32_e32 v44, 1.0, v44
	v_rcp_f32_e32 v44, v44
	v_mul_f32_e32 v29, v43, v29
	v_mul_f32_e32 v43, v45, v47
	v_mul_f32_e32 v43, v44, v43
	s_nop 0
	v_cvt_pk_bf16_f32 v43, v29, v43
	v_lshl_add_u64 v[44:45], v[30:31], 0, v[150:151]
	global_store_dwordx2 v[44:45], v[42:43], off
	s_waitcnt vmcnt(1)
; __device__ __forceinline__ float silu_mul(float g, float u) { return g * u * __builtin_amdgcn_rcpf(1.0f + __expf(-g)); }
; __device__ __forceinline__ unsigned pk2(float lo, float hi) { return pg8::cvt_pk_bf16(lo, hi); }
; __device__ __forceinline__ void ret_output(Frame& F, const Trunk& T, int layer) {
;     ...
;     for (int it = F.gw; it < 256 * 8; it += F.NGW) {
;     ...
;         for (int half = 0; half < 2; ++half) {
;     ...
;             for (int nn = 0; nn < 4; ++nn) { const int col = h * 64 + 16 * nn + 4 * quad; const u32x2 gw = *(const u32x2*)(proj + qrow * NIN + C_GR + col);
;                 const float g0 = __uint_as_float(gw.x << 16), g1 = __uint_as_float(gw.x & 0xffff0000u), g2 = __uint_as_float(gw.y << 16), g3 = __uint_as_float(gw.y & 0xffff0000u);
;                 const f32x4 v = o[qt][nn] * rs; u32x2 w; w.x = pk2(pg8::silu_mul(g0, v[0]), pg8::silu_mul(g1, v[1])); w.y = pk2(pg8::silu_mul(g2, v[2]), pg8::silu_mul(g3, v[3]));
;                 *(u32x2*)(mix + qrow * DM + MX_R + col) = w; }
	v_lshlrev_b32_e32 v29, 16, v224
	v_pk_mul_f32 v[36:37], v[36:37], v[28:29] op_sel_hi:[1,0]
	v_pk_mul_f32 v[38:39], v[38:39], v[28:29] op_sel_hi:[1,0]
	v_mul_f32_e32 v36, v36, v29
	v_mul_f32_e32 v29, 0xbfb8aa3b, v29
	v_exp_f32_e32 v29, v29
	v_and_b32_e32 v42, 0xffff0000, v224
	v_lshlrev_b32_e32 v44, 16, v225
	v_and_b32_e32 v43, 0xffff0000, v225
	v_add_f32_e32 v29, 1.0, v29
	v_rcp_f32_e32 v29, v29
	s_nop 0
	v_mul_f32_e32 v29, v29, v36
	v_mul_f32_e32 v36, v37, v42
	v_mul_f32_e32 v37, 0xbfb8aa3b, v42
	v_exp_f32_e32 v37, v37
	s_nop 0
	v_add_f32_e32 v37, 1.0, v37
	v_rcp_f32_e32 v37, v37
	s_nop 0
	v_mul_f32_e32 v36, v37, v36
	v_mul_f32_e32 v37, 0xbfb8aa3b, v44
	s_nop 0
	v_cvt_pk_bf16_f32 v36, v29, v36
	v_mul_f32_e32 v29, v38, v44
	v_exp_f32_e32 v37, v37
	v_mul_f32_e32 v38, 0xbfb8aa3b, v43
	v_exp_f32_e32 v38, v38
	v_add_f32_e32 v37, 1.0, v37
	v_rcp_f32_e32 v37, v37
	v_add_f32_e32 v38, 1.0, v38
	v_rcp_f32_e32 v38, v38
	v_mul_f32_e32 v29, v37, v29
	v_mul_f32_e32 v37, v39, v43
	v_mul_f32_e32 v37, v38, v37
	s_nop 0
	v_cvt_pk_bf16_f32 v37, v29, v37
	v_lshl_add_u64 v[38:39], v[30:31], 0, v[152:153]
	global_store_dwordx2 v[38:39], v[36:37], off
	s_waitcnt vmcnt(2)
	v_lshlrev_b32_e32 v29, 16, v226
	v_pk_mul_f32 v[32:33], v[32:33], v[28:29] op_sel_hi:[1,0]
	v_pk_mul_f32 v[34:35], v[34:35], v[28:29] op_sel_hi:[1,0]
	v_mul_f32_e32 v32, v32, v29
	v_mul_f32_e32 v29, 0xbfb8aa3b, v29
	v_exp_f32_e32 v29, v29
	v_and_b32_e32 v36, 0xffff0000, v226
	v_lshlrev_b32_e32 v38, 16, v227
	v_and_b32_e32 v37, 0xffff0000, v227
	v_add_f32_e32 v29, 1.0, v29
	v_rcp_f32_e32 v29, v29
	s_nop 0
	v_mul_f32_e32 v29, v29, v32
	v_mul_f32_e32 v32, v33, v36
	v_mul_f32_e32 v33, 0xbfb8aa3b, v36
	v_exp_f32_e32 v33, v33
	s_nop 0
	v_add_f32_e32 v33, 1.0, v33
	v_rcp_f32_e32 v33, v33
	s_nop 0
	v_mul_f32_e32 v32, v33, v32
	v_mul_f32_e32 v33, 0xbfb8aa3b, v38
	s_nop 0
	v_cvt_pk_bf16_f32 v32, v29, v32
	v_mul_f32_e32 v29, v34, v38
	v_exp_f32_e32 v33, v33
	v_mul_f32_e32 v34, 0xbfb8aa3b, v37
	v_exp_f32_e32 v34, v34
	v_add_f32_e32 v33, 1.0, v33
	v_rcp_f32_e32 v33, v33
	v_add_f32_e32 v34, 1.0, v34
	v_rcp_f32_e32 v34, v34
	v_mul_f32_e32 v29, v33, v29
	v_mul_f32_e32 v33, v35, v37
	v_mul_f32_e32 v33, v34, v33
	s_nop 0
	v_cvt_pk_bf16_f32 v33, v29, v33
	v_lshl_add_u64 v[34:35], v[30:31], 0, v[154:155]
	global_store_dwordx2 v[34:35], v[32:33], off
	s_waitcnt vmcnt(3)
	v_lshlrev_b32_e32 v29, 16, v228
	v_pk_mul_f32 v[26:27], v[26:27], v[28:29] op_sel_hi:[1,0]
	v_pk_mul_f32 v[24:25], v[24:25], v[28:29] op_sel_hi:[1,0]
	v_mul_f32_e32 v28, 0xbfb8aa3b, v29
	v_exp_f32_e32 v28, v28
	v_and_b32_e32 v32, 0xffff0000, v228
	v_mul_f32_e32 v24, v24, v29
	v_mul_f32_e32 v25, v25, v32
	v_add_f32_e32 v28, 1.0, v28
	v_rcp_f32_e32 v28, v28
	v_lshlrev_b32_e32 v34, 16, v229
	v_and_b32_e32 v33, 0xffff0000, v229
	v_mul_f32_e32 v24, v28, v24
	v_mul_f32_e32 v28, 0xbfb8aa3b, v32
	v_exp_f32_e32 v28, v28
	s_nop 0
	v_add_f32_e32 v28, 1.0, v28
	v_rcp_f32_e32 v28, v28
	s_nop 0
	v_mul_f32_e32 v25, v28, v25
	s_nop 0
	v_cvt_pk_bf16_f32 v24, v24, v25
	v_mul_f32_e32 v25, v26, v34
	v_mul_f32_e32 v26, 0xbfb8aa3b, v34
	v_exp_f32_e32 v26, v26
	s_nop 0
	v_add_f32_e32 v26, 1.0, v26
	v_rcp_f32_e32 v26, v26
	s_nop 0
	v_mul_f32_e32 v25, v26, v25
	v_mul_f32_e32 v26, v27, v33
	v_mul_f32_e32 v27, 0xbfb8aa3b, v33
	v_exp_f32_e32 v27, v27
	s_nop 0
	v_add_f32_e32 v27, 1.0, v27
	v_rcp_f32_e32 v27, v27
	s_nop 0
	v_mul_f32_e32 v26, v27, v26
	s_nop 0
	v_cvt_pk_bf16_f32 v25, v25, v26
	v_lshl_add_u64 v[26:27], v[30:31], 0, v[166:167]
	global_store_dwordx2 v[26:27], v[24:25], off
	s_cbranch_vccz .LBB0_725
	s_add_i32 s4, s4, s22
	s_cmpk_gt_i32 s4, 0x7ff
	s_cbranch_scc0 .LBB0_724
